# loop-edge edit: back-edge SALU block of the five GEMM main loops hoisted above the closing s_barrier
# baseline (speedup 1.0000x reference)
; #define PG8_STAGE(bufoff, gbase, voff) do { _Pragma("unroll") for (int _i = 0; _i < 2; ++_i) \
;         __builtin_amdgcn_global_load_lds((const unsigned*)((const char*)(gbase) + (voff)[_i]), (LAS unsigned*)(lds + (bufoff) + ldsw + _i * 8192), 16, 0, 0); } while (0)
; #define PG8_LDA(dst, b, h) do { _Pragma("unroll") for (int m = 0; m < 4; ++m) _Pragma("unroll") for (int k = 0; k < 2; ++k) dst[m][k] = *(const LAS bf16x8*)(lds + PG8_SA(b, h) + aoff + m * 2048 + k * 1024); } while (0)
; #define PG8_LDB(dst, b, h) do { _Pragma("unroll") for (int n = 0; n < 2; ++n) _Pragma("unroll") for (int k = 0; k < 2; ++k) dst[n][k] = *(const LAS bf16x8*)(lds + PG8_SB(b, h) + boff + n * 2048 + k * 1024); } while (0)
; #define PG8_MMA(ai, bj, At, Bt) do { __builtin_amdgcn_s_setprio(1); _Pragma("unroll") for (int m = 0; m < 4; ++m) _Pragma("unroll") for (int n = 0; n < 2; ++n) _Pragma("unroll") for (int k = 0; k < 2; ++k) \
;         acc[ai][bj][m][n] = __builtin_amdgcn_mfma_f32_16x16x32_bf16(Bt[n][k], At[m][k], acc[ai][bj][m][n], 0, 0, 0); __builtin_amdgcn_s_setprio(0); } while (0)
; #define PG8_WAIT_V(n) asm volatile("s_waitcnt vmcnt(" #n ")" ::: "memory")
; #define PG8_WAIT_L(n) asm volatile("s_waitcnt lgkmcnt(" #n ")" ::: "memory")
; #define PG8_BAR __builtin_amdgcn_s_barrier()
; #define PG8_SCHED __builtin_amdgcn_sched_barrier(0)
; template <class Epi, class Sched>
; __device__ __forceinline__ void gemm_phase(LAS unsigned char* lds, const Gemm g, const Sched& S, const Epi& E, float* part, int wave) {
;     ...
;         for (int t = 0; t < nt; t += 2) {
;             const bool last = (t == nt - 2);
;             const char* a1 = cA + (size_t)(t + 1) * kstep;
;             const char* a2 = last ? nA : cA + (size_t)(t + 2) * kstep; const char* b2 = last ? nB : cB + (size_t)(t + 2) * kstep;
;             const char* a3 = a2 + kstep; const char* b3 = b2 + kstep;
;             PG8_LDB(B0, 0, 0); PG8_LDB(B1, 0, 1); PG8_SCHED; PG8_LDA(At, 0, 0); PG8_STAGE(PG8_SA(1, 1), a1 + hstep, voffA);
;             PG8_WAIT_V(8); PG8_WAIT_L(0); PG8_BAR; PG8_MMA(0, 0, At, B0); PG8_MMA(0, 1, At, B1); PG8_BAR; PG8_SCHED;
;             PG8_LDA(At, 0, 1); PG8_STAGE(PG8_SB(0, 0), b2, voffB); PG8_STAGE(PG8_SB(0, 1), b2 + hstep, voffB); PG8_STAGE(PG8_SA(0, 0), a2, voffA);
;             PG8_WAIT_V(8); PG8_WAIT_L(0); PG8_BAR; PG8_MMA(1, 0, At, B0); PG8_MMA(1, 1, At, B1); PG8_BAR; PG8_SCHED;
.LBB0_128:
	ds_read_b128 v[162:165], v187
	ds_read_b128 v[166:169], v187 offset:1024
	ds_read_b128 v[170:173], v187 offset:2048
	ds_read_b128 v[190:193], v187 offset:3072
	ds_read_b128 v[194:197], v188
	ds_read_b128 v[198:201], v188 offset:1024
	ds_read_b128 v[202:205], v188 offset:2048
	ds_read_b128 v[206:209], v188 offset:3072
	s_add_i32 s67, s29, 2
	s_add_u32 s34, s30, 0xfff00080
	s_addc_u32 s35, s31, -1
	s_cmp_eq_u32 s22, s29
	s_cselect_b32 s37, s77, s35
	s_cselect_b32 s36, s76, s34
	s_cselect_b32 s35, s79, s27
	s_cselect_b32 s34, s78, s23
	v_lshl_add_u64 v[174:175], s[30:31], 0, v[158:159]
	s_add_i32 m0, s96, 0xc000
	ds_read_b128 v[210:213], v186
	ds_read_b128 v[214:217], v186 offset:1024
	ds_read_b128 v[218:221], v186 offset:2048
	ds_read_b128 v[222:225], v186 offset:3072
	ds_read_b128 v[226:229], v186 offset:4096
	ds_read_b128 v[230:233], v186 offset:5120
	ds_read_b128 v[234:237], v186 offset:6144
	ds_read_b128 v[238:241], v186 offset:7168
	global_load_lds_dwordx4 v[174:175], off
	v_lshl_add_u64 v[174:175], s[30:31], 0, v[156:157]
	s_add_i32 m0, s96, 0xe000
	s_nop 0
	global_load_lds_dwordx4 v[174:175], off
	s_waitcnt vmcnt(8)
	s_waitcnt lgkmcnt(0)
	s_barrier
	s_setprio 1
	s_waitcnt lgkmcnt(0)
	v_mfma_f32_16x16x32_bf16 v[124:127], v[162:165], v[210:213], v[124:127]
	v_mfma_f32_16x16x32_bf16 v[120:123], v[170:173], v[210:213], v[120:123]
	v_mfma_f32_16x16x32_bf16 v[116:119], v[162:165], v[218:221], v[116:119]
	v_mfma_f32_16x16x32_bf16 v[112:115], v[170:173], v[218:221], v[112:115]
	v_mfma_f32_16x16x32_bf16 v[108:111], v[162:165], v[226:229], v[108:111]
	v_mfma_f32_16x16x32_bf16 v[104:107], v[170:173], v[226:229], v[104:107]
	v_mfma_f32_16x16x32_bf16 v[100:103], v[162:165], v[234:237], v[100:103]
	v_mfma_f32_16x16x32_bf16 v[96:99], v[170:173], v[234:237], v[96:99]
	v_mfma_f32_16x16x32_bf16 v[124:127], v[166:169], v[214:217], v[124:127]
	v_mfma_f32_16x16x32_bf16 v[120:123], v[190:193], v[214:217], v[120:123]
	v_mfma_f32_16x16x32_bf16 v[116:119], v[166:169], v[222:225], v[116:119]
	v_mfma_f32_16x16x32_bf16 v[112:115], v[190:193], v[222:225], v[112:115]
	v_mfma_f32_16x16x32_bf16 v[108:111], v[166:169], v[230:233], v[108:111]
	v_mfma_f32_16x16x32_bf16 v[104:107], v[190:193], v[230:233], v[104:107]
	v_mfma_f32_16x16x32_bf16 v[100:103], v[166:169], v[238:241], v[100:103]
	v_mfma_f32_16x16x32_bf16 v[96:99], v[190:193], v[238:241], v[96:99]
	s_setprio 0
	s_setprio 1
	v_mfma_f32_16x16x32_bf16 v[92:95], v[194:197], v[210:213], v[92:95]
	v_mfma_f32_16x16x32_bf16 v[88:91], v[202:205], v[210:213], v[88:91]
	v_mfma_f32_16x16x32_bf16 v[84:87], v[194:197], v[218:221], v[84:87]
	v_mfma_f32_16x16x32_bf16 v[80:83], v[202:205], v[218:221], v[80:83]
	v_mfma_f32_16x16x32_bf16 v[76:79], v[194:197], v[226:229], v[76:79]
	v_mfma_f32_16x16x32_bf16 v[72:75], v[202:205], v[226:229], v[72:75]
	v_mfma_f32_16x16x32_bf16 v[68:71], v[194:197], v[234:237], v[68:71]
	v_mfma_f32_16x16x32_bf16 v[64:67], v[202:205], v[234:237], v[64:67]
	v_mfma_f32_16x16x32_bf16 v[92:95], v[198:201], v[214:217], v[92:95]
	v_mfma_f32_16x16x32_bf16 v[88:91], v[206:209], v[214:217], v[88:91]
	v_mfma_f32_16x16x32_bf16 v[84:87], v[198:201], v[222:225], v[84:87]
	v_mfma_f32_16x16x32_bf16 v[80:83], v[206:209], v[222:225], v[80:83]
	v_mfma_f32_16x16x32_bf16 v[76:79], v[198:201], v[230:233], v[76:79]
	v_mfma_f32_16x16x32_bf16 v[72:75], v[206:209], v[230:233], v[72:75]
	v_mfma_f32_16x16x32_bf16 v[68:71], v[198:201], v[238:241], v[68:71]
	v_mfma_f32_16x16x32_bf16 v[64:67], v[206:209], v[238:241], v[64:67]
	s_setprio 0
	s_barrier
	s_add_i32 s29, s16, s91
	v_lshl_add_u64 v[174:175], s[34:35], 0, v[130:131]
	s_mov_b32 m0, s29
	ds_read_b128 v[210:213], v186 offset:16384
	ds_read_b128 v[214:217], v186 offset:17408
	ds_read_b128 v[218:221], v186 offset:18432
	ds_read_b128 v[222:225], v186 offset:19456
	ds_read_b128 v[226:229], v186 offset:20480
	ds_read_b128 v[230:233], v186 offset:21504
	ds_read_b128 v[234:237], v186 offset:22528
	ds_read_b128 v[238:241], v186 offset:23552
	global_load_lds_dwordx4 v[174:175], off
	s_add_i32 m0, s29, 0x2000
	s_add_u32 s80, s34, 0x100000
	v_lshl_add_u64 v[242:243], s[34:35], 0, v[134:135]
	s_addc_u32 s81, s35, 0
	s_add_i32 s29, s17, s91
	global_load_lds_dwordx4 v[242:243], off
	v_lshl_add_u64 v[244:245], s[80:81], 0, v[130:131]
	s_mov_b32 m0, s29
	v_lshl_add_u64 v[246:247], s[36:37], 0, v[132:133]
	global_load_lds_dwordx4 v[244:245], off
	v_lshl_add_u64 v[244:245], s[80:81], 0, v[134:135]
	s_add_i32 m0, s29, 0x2000
	s_nop 0
	global_load_lds_dwordx4 v[244:245], off
	v_lshl_add_u64 v[244:245], s[36:37], 0, v[128:129]
	s_mov_b32 m0, s96
	s_nop 0
	global_load_lds_dwordx4 v[244:245], off
	s_mov_b32 m0, s39
	s_nop 0
	global_load_lds_dwordx4 v[246:247], off
	s_waitcnt vmcnt(8)
	s_waitcnt lgkmcnt(0)
	s_barrier
; #define PG8_STAGE(bufoff, gbase, voff) do { _Pragma("unroll") for (int _i = 0; _i < 2; ++_i) \
;         __builtin_amdgcn_global_load_lds((const unsigned*)((const char*)(gbase) + (voff)[_i]), (LAS unsigned*)(lds + (bufoff) + ldsw + _i * 8192), 16, 0, 0); } while (0)
; #define PG8_LDA(dst, b, h) do { _Pragma("unroll") for (int m = 0; m < 4; ++m) _Pragma("unroll") for (int k = 0; k < 2; ++k) dst[m][k] = *(const LAS bf16x8*)(lds + PG8_SA(b, h) + aoff + m * 2048 + k * 1024); } while (0)
; #define PG8_LDB(dst, b, h) do { _Pragma("unroll") for (int n = 0; n < 2; ++n) _Pragma("unroll") for (int k = 0; k < 2; ++k) dst[n][k] = *(const LAS bf16x8*)(lds + PG8_SB(b, h) + boff + n * 2048 + k * 1024); } while (0)
; #define PG8_MMA(ai, bj, At, Bt) do { __builtin_amdgcn_s_setprio(1); _Pragma("unroll") for (int m = 0; m < 4; ++m) _Pragma("unroll") for (int n = 0; n < 2; ++n) _Pragma("unroll") for (int k = 0; k < 2; ++k) \
;         acc[ai][bj][m][n] = __builtin_amdgcn_mfma_f32_16x16x32_bf16(Bt[n][k], At[m][k], acc[ai][bj][m][n], 0, 0, 0); __builtin_amdgcn_s_setprio(0); } while (0)
; #define PG8_WAIT_V(n) asm volatile("s_waitcnt vmcnt(" #n ")" ::: "memory")
; #define PG8_WAIT_L(n) asm volatile("s_waitcnt lgkmcnt(" #n ")" ::: "memory")
; #define PG8_BAR __builtin_amdgcn_s_barrier()
; #define PG8_SCHED __builtin_amdgcn_sched_barrier(0)
; template <class Epi, class Sched>
; __device__ __forceinline__ void gemm_phase(LAS unsigned char* lds, const Gemm g, const Sched& S, const Epi& E, float* part, int wave) {
;     ...
;             PG8_WAIT_V(8); PG8_WAIT_L(0); PG8_BAR; PG8_MMA(1, 0, At, B0); PG8_MMA(1, 1, At, B1); PG8_BAR; PG8_SCHED;
;             PG8_LDB(B0, 1, 0); PG8_LDB(B1, 1, 1); PG8_SCHED; PG8_LDA(At, 1, 0); PG8_STAGE(PG8_SA(0, 1), a2 + hstep, voffA);
;             PG8_WAIT_V(8); PG8_WAIT_L(0); PG8_BAR; PG8_MMA(0, 0, At, B0); PG8_MMA(0, 1, At, B1); PG8_BAR; PG8_SCHED;
	s_setprio 1
	s_waitcnt lgkmcnt(0)
	v_mfma_f32_16x16x32_bf16 v[60:63], v[162:165], v[210:213], v[60:63]
	v_mfma_f32_16x16x32_bf16 v[56:59], v[170:173], v[210:213], v[56:59]
	v_mfma_f32_16x16x32_bf16 v[52:55], v[162:165], v[218:221], v[52:55]
	v_mfma_f32_16x16x32_bf16 v[48:51], v[170:173], v[218:221], v[48:51]
	v_mfma_f32_16x16x32_bf16 v[44:47], v[162:165], v[226:229], v[44:47]
	v_mfma_f32_16x16x32_bf16 v[40:43], v[170:173], v[226:229], v[40:43]
	v_mfma_f32_16x16x32_bf16 v[36:39], v[162:165], v[234:237], v[36:39]
	v_mfma_f32_16x16x32_bf16 v[32:35], v[170:173], v[234:237], v[32:35]
	v_mfma_f32_16x16x32_bf16 v[60:63], v[166:169], v[214:217], v[60:63]
	v_mfma_f32_16x16x32_bf16 v[56:59], v[190:193], v[214:217], v[56:59]
	v_mfma_f32_16x16x32_bf16 v[52:55], v[166:169], v[222:225], v[52:55]
	v_mfma_f32_16x16x32_bf16 v[48:51], v[190:193], v[222:225], v[48:51]
	v_mfma_f32_16x16x32_bf16 v[44:47], v[166:169], v[230:233], v[44:47]
	v_mfma_f32_16x16x32_bf16 v[40:43], v[190:193], v[230:233], v[40:43]
	v_mfma_f32_16x16x32_bf16 v[36:39], v[166:169], v[238:241], v[36:39]
	v_mfma_f32_16x16x32_bf16 v[32:35], v[190:193], v[238:241], v[32:35]
	s_setprio 0
	s_setprio 1
	v_mfma_f32_16x16x32_bf16 v[28:31], v[194:197], v[210:213], v[28:31]
	v_mfma_f32_16x16x32_bf16 v[24:27], v[202:205], v[210:213], v[24:27]
	v_mfma_f32_16x16x32_bf16 v[20:23], v[194:197], v[218:221], v[20:23]
	v_mfma_f32_16x16x32_bf16 v[16:19], v[202:205], v[218:221], v[16:19]
	v_mfma_f32_16x16x32_bf16 v[12:15], v[194:197], v[226:229], v[12:15]
	v_mfma_f32_16x16x32_bf16 v[8:11], v[202:205], v[226:229], v[8:11]
	v_mfma_f32_16x16x32_bf16 v[4:7], v[194:197], v[234:237], v[4:7]
	v_mfma_f32_16x16x32_bf16 v[0:3], v[202:205], v[234:237], v[0:3]
	v_mfma_f32_16x16x32_bf16 v[28:31], v[198:201], v[214:217], v[28:31]
	v_mfma_f32_16x16x32_bf16 v[24:27], v[206:209], v[214:217], v[24:27]
	v_mfma_f32_16x16x32_bf16 v[20:23], v[198:201], v[222:225], v[20:23]
	v_mfma_f32_16x16x32_bf16 v[16:19], v[206:209], v[222:225], v[16:19]
	v_mfma_f32_16x16x32_bf16 v[12:15], v[198:201], v[230:233], v[12:15]
	v_mfma_f32_16x16x32_bf16 v[8:11], v[206:209], v[230:233], v[8:11]
	v_mfma_f32_16x16x32_bf16 v[4:7], v[198:201], v[238:241], v[4:7]
	v_mfma_f32_16x16x32_bf16 v[0:3], v[206:209], v[238:241], v[0:3]
	s_setprio 0
	s_barrier
	s_add_i32 s29, 0, 0x18000
	v_add_u32_e32 v189, s29, v177
	s_add_i32 s73, 0, 0x1c000
	ds_read_b128 v[162:165], v189
	ds_read_b128 v[166:169], v189 offset:1024
	ds_read_b128 v[170:173], v189 offset:2048
	ds_read_b128 v[190:193], v189 offset:3072
	v_add_u32_e32 v189, s73, v177
	ds_read_b128 v[194:197], v189
	ds_read_b128 v[198:201], v189 offset:1024
	ds_read_b128 v[202:205], v189 offset:2048
	ds_read_b128 v[206:209], v189 offset:3072
	s_add_u32 s36, s36, 0x100000
	s_addc_u32 s37, s37, 0
	s_mov_b32 m0, s4
	v_lshl_add_u64 v[248:249], s[36:37], 0, v[128:129]
	ds_read_b128 v[210:213], v186 offset:32768
	ds_read_b128 v[214:217], v186 offset:33792
	ds_read_b128 v[218:221], v186 offset:34816
	ds_read_b128 v[222:225], v186 offset:35840
	ds_read_b128 v[226:229], v186 offset:36864
	ds_read_b128 v[230:233], v186 offset:37888
	ds_read_b128 v[234:237], v186 offset:38912
	ds_read_b128 v[238:241], v186 offset:39936
	global_load_lds_dwordx4 v[248:249], off
	v_lshl_add_u64 v[248:249], s[36:37], 0, v[132:133]
	s_mov_b32 m0, s5
	s_nop 0
	global_load_lds_dwordx4 v[248:249], off
	s_waitcnt vmcnt(8)
	s_waitcnt lgkmcnt(0)
	s_barrier
	s_setprio 1
	s_waitcnt lgkmcnt(0)
	v_mfma_f32_16x16x32_bf16 v[124:127], v[162:165], v[210:213], v[124:127]
	v_mfma_f32_16x16x32_bf16 v[120:123], v[170:173], v[210:213], v[120:123]
	v_mfma_f32_16x16x32_bf16 v[116:119], v[162:165], v[218:221], v[116:119]
	v_mfma_f32_16x16x32_bf16 v[112:115], v[170:173], v[218:221], v[112:115]
	v_mfma_f32_16x16x32_bf16 v[108:111], v[162:165], v[226:229], v[108:111]
	v_mfma_f32_16x16x32_bf16 v[104:107], v[170:173], v[226:229], v[104:107]
	v_mfma_f32_16x16x32_bf16 v[100:103], v[162:165], v[234:237], v[100:103]
	v_mfma_f32_16x16x32_bf16 v[96:99], v[170:173], v[234:237], v[96:99]
	v_mfma_f32_16x16x32_bf16 v[124:127], v[166:169], v[214:217], v[124:127]
	v_mfma_f32_16x16x32_bf16 v[120:123], v[190:193], v[214:217], v[120:123]
	v_mfma_f32_16x16x32_bf16 v[116:119], v[166:169], v[222:225], v[116:119]
	v_mfma_f32_16x16x32_bf16 v[112:115], v[190:193], v[222:225], v[112:115]
	v_mfma_f32_16x16x32_bf16 v[108:111], v[166:169], v[230:233], v[108:111]
	v_mfma_f32_16x16x32_bf16 v[104:107], v[190:193], v[230:233], v[104:107]
	v_mfma_f32_16x16x32_bf16 v[100:103], v[166:169], v[238:241], v[100:103]
	v_mfma_f32_16x16x32_bf16 v[96:99], v[190:193], v[238:241], v[96:99]
	s_setprio 0
	s_setprio 1
	v_mfma_f32_16x16x32_bf16 v[92:95], v[194:197], v[210:213], v[92:95]
	v_mfma_f32_16x16x32_bf16 v[88:91], v[202:205], v[210:213], v[88:91]
	v_mfma_f32_16x16x32_bf16 v[84:87], v[194:197], v[218:221], v[84:87]
	v_mfma_f32_16x16x32_bf16 v[80:83], v[202:205], v[218:221], v[80:83]
	v_mfma_f32_16x16x32_bf16 v[76:79], v[194:197], v[226:229], v[76:79]
	v_mfma_f32_16x16x32_bf16 v[72:75], v[202:205], v[226:229], v[72:75]
	v_mfma_f32_16x16x32_bf16 v[68:71], v[194:197], v[234:237], v[68:71]
	v_mfma_f32_16x16x32_bf16 v[64:67], v[202:205], v[234:237], v[64:67]
	v_mfma_f32_16x16x32_bf16 v[92:95], v[198:201], v[214:217], v[92:95]
	v_mfma_f32_16x16x32_bf16 v[88:91], v[206:209], v[214:217], v[88:91]
	v_mfma_f32_16x16x32_bf16 v[84:87], v[198:201], v[222:225], v[84:87]
	v_mfma_f32_16x16x32_bf16 v[80:83], v[206:209], v[222:225], v[80:83]
	v_mfma_f32_16x16x32_bf16 v[76:79], v[198:201], v[230:233], v[76:79]
	v_mfma_f32_16x16x32_bf16 v[72:75], v[206:209], v[230:233], v[72:75]
	v_mfma_f32_16x16x32_bf16 v[68:71], v[198:201], v[238:241], v[68:71]
	v_mfma_f32_16x16x32_bf16 v[64:67], v[206:209], v[238:241], v[64:67]
	s_setprio 0
	s_barrier
; #define PG8_STAGE(bufoff, gbase, voff) do { _Pragma("unroll") for (int _i = 0; _i < 2; ++_i) \
;         __builtin_amdgcn_global_load_lds((const unsigned*)((const char*)(gbase) + (voff)[_i]), (LAS unsigned*)(lds + (bufoff) + ldsw + _i * 8192), 16, 0, 0); } while (0)
; #define PG8_LDA(dst, b, h) do { _Pragma("unroll") for (int m = 0; m < 4; ++m) _Pragma("unroll") for (int k = 0; k < 2; ++k) dst[m][k] = *(const LAS bf16x8*)(lds + PG8_SA(b, h) + aoff + m * 2048 + k * 1024); } while (0)
; #define PG8_MMA(ai, bj, At, Bt) do { __builtin_amdgcn_s_setprio(1); _Pragma("unroll") for (int m = 0; m < 4; ++m) _Pragma("unroll") for (int n = 0; n < 2; ++n) _Pragma("unroll") for (int k = 0; k < 2; ++k) \
;         acc[ai][bj][m][n] = __builtin_amdgcn_mfma_f32_16x16x32_bf16(Bt[n][k], At[m][k], acc[ai][bj][m][n], 0, 0, 0); __builtin_amdgcn_s_setprio(0); } while (0)
; #define PG8_WAIT_V(n) asm volatile("s_waitcnt vmcnt(" #n ")" ::: "memory")
; #define PG8_WAIT_L(n) asm volatile("s_waitcnt lgkmcnt(" #n ")" ::: "memory")
; #define PG8_BAR __builtin_amdgcn_s_barrier()
; #define PG8_SCHED __builtin_amdgcn_sched_barrier(0)
; template <class Epi, class Sched>
; __device__ __forceinline__ void gemm_phase(LAS unsigned char* lds, const Gemm g, const Sched& S, const Epi& E, float* part, int wave) {
;     ...
;             PG8_LDA(At, 1, 1); PG8_STAGE(PG8_SB(1, 0), b3, voffB); PG8_STAGE(PG8_SB(1, 1), b3 + hstep, voffB); PG8_STAGE(PG8_SA(1, 0), a3, voffA);
;             PG8_WAIT_V(8); PG8_WAIT_L(0); PG8_BAR; PG8_MMA(1, 0, At, B0); PG8_MMA(1, 1, At, B1); PG8_BAR; PG8_SCHED;
;         }
	s_add_i32 s29, s29, s91
	v_lshl_add_u64 v[174:175], v[174:175], 0, s[62:63]
	s_mov_b32 m0, s29
	ds_read_b128 v[210:213], v186 offset:49152
	ds_read_b128 v[214:217], v186 offset:50176
	ds_read_b128 v[218:221], v186 offset:51200
	ds_read_b128 v[222:225], v186 offset:52224
	ds_read_b128 v[226:229], v186 offset:53248
	ds_read_b128 v[230:233], v186 offset:54272
	ds_read_b128 v[234:237], v186 offset:55296
	ds_read_b128 v[238:241], v186 offset:56320
	global_load_lds_dwordx4 v[174:175], off
	s_add_i32 m0, s29, 0x2000
	s_add_u32 s34, s34, 0x100080
	v_lshl_add_u64 v[174:175], v[242:243], 0, s[62:63]
	s_addc_u32 s35, s35, 0
	s_add_i32 s29, s73, s91
	global_load_lds_dwordx4 v[174:175], off
	v_lshl_add_u64 v[174:175], s[34:35], 0, v[130:131]
	s_mov_b32 m0, s29
	s_nop 0
	global_load_lds_dwordx4 v[174:175], off
	v_lshl_add_u64 v[174:175], s[34:35], 0, v[134:135]
	s_add_i32 m0, s29, 0x2000
	s_nop 0
	global_load_lds_dwordx4 v[174:175], off
	v_lshl_add_u64 v[174:175], v[244:245], 0, s[62:63]
	s_mov_b32 m0, s33
	s_nop 0
	global_load_lds_dwordx4 v[174:175], off
	v_lshl_add_u64 v[174:175], v[246:247], 0, s[62:63]
	s_mov_b32 m0, s8
	s_nop 0
	global_load_lds_dwordx4 v[174:175], off
	s_waitcnt vmcnt(8)
	s_waitcnt lgkmcnt(0)
	s_barrier
	s_setprio 1
	s_waitcnt lgkmcnt(0)
	v_mfma_f32_16x16x32_bf16 v[60:63], v[162:165], v[210:213], v[60:63]
	v_mfma_f32_16x16x32_bf16 v[56:59], v[170:173], v[210:213], v[56:59]
	v_mfma_f32_16x16x32_bf16 v[52:55], v[162:165], v[218:221], v[52:55]
	v_mfma_f32_16x16x32_bf16 v[48:51], v[170:173], v[218:221], v[48:51]
	v_mfma_f32_16x16x32_bf16 v[44:47], v[162:165], v[226:229], v[44:47]
	v_mfma_f32_16x16x32_bf16 v[40:43], v[170:173], v[226:229], v[40:43]
	v_mfma_f32_16x16x32_bf16 v[36:39], v[162:165], v[234:237], v[36:39]
	v_mfma_f32_16x16x32_bf16 v[32:35], v[170:173], v[234:237], v[32:35]
	v_mfma_f32_16x16x32_bf16 v[60:63], v[166:169], v[214:217], v[60:63]
	v_mfma_f32_16x16x32_bf16 v[56:59], v[190:193], v[214:217], v[56:59]
	v_mfma_f32_16x16x32_bf16 v[52:55], v[166:169], v[222:225], v[52:55]
	v_mfma_f32_16x16x32_bf16 v[48:51], v[190:193], v[222:225], v[48:51]
	v_mfma_f32_16x16x32_bf16 v[44:47], v[166:169], v[230:233], v[44:47]
	v_mfma_f32_16x16x32_bf16 v[40:43], v[190:193], v[230:233], v[40:43]
	v_mfma_f32_16x16x32_bf16 v[36:39], v[166:169], v[238:241], v[36:39]
	v_mfma_f32_16x16x32_bf16 v[32:35], v[190:193], v[238:241], v[32:35]
	s_setprio 0
	s_setprio 1
	v_mfma_f32_16x16x32_bf16 v[28:31], v[194:197], v[210:213], v[28:31]
	v_mfma_f32_16x16x32_bf16 v[24:27], v[202:205], v[210:213], v[24:27]
	v_mfma_f32_16x16x32_bf16 v[20:23], v[194:197], v[218:221], v[20:23]
	v_mfma_f32_16x16x32_bf16 v[16:19], v[202:205], v[218:221], v[16:19]
	v_mfma_f32_16x16x32_bf16 v[12:15], v[194:197], v[226:229], v[12:15]
	v_mfma_f32_16x16x32_bf16 v[8:11], v[202:205], v[226:229], v[8:11]
	v_mfma_f32_16x16x32_bf16 v[4:7], v[194:197], v[234:237], v[4:7]
	v_mfma_f32_16x16x32_bf16 v[0:3], v[202:205], v[234:237], v[0:3]
	v_mfma_f32_16x16x32_bf16 v[28:31], v[198:201], v[214:217], v[28:31]
	v_mfma_f32_16x16x32_bf16 v[24:27], v[206:209], v[214:217], v[24:27]
	v_mfma_f32_16x16x32_bf16 v[20:23], v[198:201], v[222:225], v[20:23]
	v_mfma_f32_16x16x32_bf16 v[16:19], v[206:209], v[222:225], v[16:19]
	v_mfma_f32_16x16x32_bf16 v[12:15], v[198:201], v[230:233], v[12:15]
	v_mfma_f32_16x16x32_bf16 v[8:11], v[206:209], v[230:233], v[8:11]
	v_mfma_f32_16x16x32_bf16 v[4:7], v[198:201], v[238:241], v[4:7]
	v_mfma_f32_16x16x32_bf16 v[0:3], v[206:209], v[238:241], v[0:3]
	s_add_u32 s23, s23, 0x100
	s_addc_u32 s27, s27, 0
	s_add_u32 s30, s30, 0x100
	s_addc_u32 s31, s31, 0
	s_cmp_ge_i32 s67, s3
	s_mov_b32 s29, s67
	s_setprio 0
	s_barrier
	s_cbranch_scc0 .LBB0_128
	s_and_b64 vcc, exec, s[64:65]
	s_cbranch_vccz .LBB0_134

; #define PG8_STAGE(bufoff, gbase, voff) do { _Pragma("unroll") for (int _i = 0; _i < 2; ++_i) \
;         __builtin_amdgcn_global_load_lds((const unsigned*)((const char*)(gbase) + (voff)[_i]), (LAS unsigned*)(lds + (bufoff) + ldsw + _i * 8192), 16, 0, 0); } while (0)
; #define PG8_LDA(dst, b, h) do { _Pragma("unroll") for (int m = 0; m < 4; ++m) _Pragma("unroll") for (int k = 0; k < 2; ++k) dst[m][k] = *(const LAS bf16x8*)(lds + PG8_SA(b, h) + aoff + m * 2048 + k * 1024); } while (0)
; #define PG8_LDB(dst, b, h) do { _Pragma("unroll") for (int n = 0; n < 2; ++n) _Pragma("unroll") for (int k = 0; k < 2; ++k) dst[n][k] = *(const LAS bf16x8*)(lds + PG8_SB(b, h) + boff + n * 2048 + k * 1024); } while (0)
; #define PG8_MMA(ai, bj, At, Bt) do { __builtin_amdgcn_s_setprio(1); _Pragma("unroll") for (int m = 0; m < 4; ++m) _Pragma("unroll") for (int n = 0; n < 2; ++n) _Pragma("unroll") for (int k = 0; k < 2; ++k) \
;         acc[ai][bj][m][n] = __builtin_amdgcn_mfma_f32_16x16x32_bf16(Bt[n][k], At[m][k], acc[ai][bj][m][n], 0, 0, 0); __builtin_amdgcn_s_setprio(0); } while (0)
; #define PG8_WAIT_V(n) asm volatile("s_waitcnt vmcnt(" #n ")" ::: "memory")
; #define PG8_WAIT_L(n) asm volatile("s_waitcnt lgkmcnt(" #n ")" ::: "memory")
; #define PG8_BAR __builtin_amdgcn_s_barrier()
; #define PG8_SCHED __builtin_amdgcn_sched_barrier(0)
; template <class Epi, class Sched>
; __device__ __forceinline__ void gemm_phase(LAS unsigned char* lds, const Gemm g, const Sched& S, const Epi& E, float* part, int wave) {
;     ...
;         for (int t = 0; t < nt; t += 2) {
;             const bool last = (t == nt - 2);
;             const char* a1 = cA + (size_t)(t + 1) * kstep;
;             const char* a2 = last ? nA : cA + (size_t)(t + 2) * kstep; const char* b2 = last ? nB : cB + (size_t)(t + 2) * kstep;
;             const char* a3 = a2 + kstep; const char* b3 = b2 + kstep;
;             PG8_LDB(B0, 0, 0); PG8_LDB(B1, 0, 1); PG8_SCHED; PG8_LDA(At, 0, 0); PG8_STAGE(PG8_SA(1, 1), a1 + hstep, voffA);
;             PG8_WAIT_V(8); PG8_WAIT_L(0); PG8_BAR; PG8_MMA(0, 0, At, B0); PG8_MMA(0, 1, At, B1); PG8_BAR; PG8_SCHED;
;             PG8_LDA(At, 0, 1); PG8_STAGE(PG8_SB(0, 0), b2, voffB); PG8_STAGE(PG8_SB(0, 1), b2 + hstep, voffB); PG8_STAGE(PG8_SA(0, 0), a2, voffA);
;             PG8_WAIT_V(8); PG8_WAIT_L(0); PG8_BAR; PG8_MMA(1, 0, At, B0); PG8_MMA(1, 1, At, B1); PG8_BAR; PG8_SCHED;
.LBB0_825:
	ds_read_b128 v[142:145], v151
	ds_read_b128 v[154:157], v151 offset:1024
	ds_read_b128 v[158:161], v151 offset:2048
	ds_read_b128 v[162:165], v151 offset:3072
	ds_read_b128 v[166:169], v152
	ds_read_b128 v[170:173], v152 offset:1024
	ds_read_b128 v[174:177], v152 offset:2048
	ds_read_b128 v[178:181], v152 offset:3072
	s_add_u32 s34, s30, 0xfffe0080
	s_addc_u32 s35, s31, -1
	s_cmp_eq_u32 s59, 4
	s_cselect_b32 s37, s23, s35
	s_cselect_b32 s36, s22, s34
	s_cselect_b32 s35, s25, s21
	s_cselect_b32 s34, s24, s19
	v_lshl_add_u64 v[146:147], s[30:31], 0, v[138:139]
	s_add_i32 m0, s27, 0xc000
	ds_read_b128 v[182:185], v153
	ds_read_b128 v[186:189], v153 offset:1024
	ds_read_b128 v[194:197], v153 offset:2048
	ds_read_b128 v[198:201], v153 offset:3072
	ds_read_b128 v[202:205], v153 offset:4096
	ds_read_b128 v[206:209], v153 offset:5120
	ds_read_b128 v[210:213], v153 offset:6144
	ds_read_b128 v[214:217], v153 offset:7168
	global_load_lds_dwordx4 v[146:147], off
	v_lshl_add_u64 v[146:147], s[30:31], 0, v[136:137]
	s_add_i32 m0, s27, 0xe000
	s_nop 0
	global_load_lds_dwordx4 v[146:147], off
	s_waitcnt vmcnt(8)
	s_waitcnt lgkmcnt(0)
	s_barrier
	s_setprio 1
	s_waitcnt lgkmcnt(0)
	v_mfma_f32_16x16x32_bf16 v[124:127], v[142:145], v[182:185], v[124:127]
	v_mfma_f32_16x16x32_bf16 v[120:123], v[158:161], v[182:185], v[120:123]
	v_mfma_f32_16x16x32_bf16 v[108:111], v[142:145], v[194:197], v[108:111]
	v_mfma_f32_16x16x32_bf16 v[104:107], v[158:161], v[194:197], v[104:107]
	v_mfma_f32_16x16x32_bf16 v[92:95], v[142:145], v[202:205], v[92:95]
	v_mfma_f32_16x16x32_bf16 v[88:91], v[158:161], v[202:205], v[88:91]
	v_mfma_f32_16x16x32_bf16 v[76:79], v[142:145], v[210:213], v[76:79]
	v_mfma_f32_16x16x32_bf16 v[72:75], v[158:161], v[210:213], v[72:75]
	v_mfma_f32_16x16x32_bf16 v[124:127], v[154:157], v[186:189], v[124:127]
	v_mfma_f32_16x16x32_bf16 v[120:123], v[162:165], v[186:189], v[120:123]
	v_mfma_f32_16x16x32_bf16 v[108:111], v[154:157], v[198:201], v[108:111]
	v_mfma_f32_16x16x32_bf16 v[104:107], v[162:165], v[198:201], v[104:107]
	v_mfma_f32_16x16x32_bf16 v[92:95], v[154:157], v[206:209], v[92:95]
	v_mfma_f32_16x16x32_bf16 v[88:91], v[162:165], v[206:209], v[88:91]
	v_mfma_f32_16x16x32_bf16 v[76:79], v[154:157], v[214:217], v[76:79]
	v_mfma_f32_16x16x32_bf16 v[72:75], v[162:165], v[214:217], v[72:75]
	s_setprio 0
	s_setprio 1
	v_mfma_f32_16x16x32_bf16 v[116:119], v[166:169], v[182:185], v[116:119]
	v_mfma_f32_16x16x32_bf16 v[112:115], v[174:177], v[182:185], v[112:115]
	v_mfma_f32_16x16x32_bf16 v[100:103], v[166:169], v[194:197], v[100:103]
	v_mfma_f32_16x16x32_bf16 v[96:99], v[174:177], v[194:197], v[96:99]
	v_mfma_f32_16x16x32_bf16 v[84:87], v[166:169], v[202:205], v[84:87]
	v_mfma_f32_16x16x32_bf16 v[80:83], v[174:177], v[202:205], v[80:83]
	v_mfma_f32_16x16x32_bf16 v[68:71], v[166:169], v[210:213], v[68:71]
	v_mfma_f32_16x16x32_bf16 v[64:67], v[174:177], v[210:213], v[64:67]
	v_mfma_f32_16x16x32_bf16 v[116:119], v[170:173], v[186:189], v[116:119]
	v_mfma_f32_16x16x32_bf16 v[112:115], v[178:181], v[186:189], v[112:115]
	v_mfma_f32_16x16x32_bf16 v[100:103], v[170:173], v[198:201], v[100:103]
	v_mfma_f32_16x16x32_bf16 v[96:99], v[178:181], v[198:201], v[96:99]
	v_mfma_f32_16x16x32_bf16 v[84:87], v[170:173], v[206:209], v[84:87]
	v_mfma_f32_16x16x32_bf16 v[80:83], v[178:181], v[206:209], v[80:83]
	v_mfma_f32_16x16x32_bf16 v[68:71], v[170:173], v[214:217], v[68:71]
	v_mfma_f32_16x16x32_bf16 v[64:67], v[178:181], v[214:217], v[64:67]
	s_setprio 0
	s_barrier
	s_add_i32 s62, s56, s91
	v_lshl_add_u64 v[146:147], s[34:35], 0, v[130:131]
	s_mov_b32 m0, s62
	ds_read_b128 v[182:185], v153 offset:16384
	ds_read_b128 v[186:189], v153 offset:17408
	ds_read_b128 v[194:197], v153 offset:18432
	ds_read_b128 v[198:201], v153 offset:19456
	ds_read_b128 v[202:205], v153 offset:20480
	ds_read_b128 v[206:209], v153 offset:21504
	ds_read_b128 v[210:213], v153 offset:22528
	ds_read_b128 v[214:217], v153 offset:23552
	global_load_lds_dwordx4 v[146:147], off
	s_add_i32 m0, s62, 0x2000
	s_add_u32 s62, s34, 0x20000
	v_lshl_add_u64 v[190:191], s[34:35], 0, v[134:135]
	s_addc_u32 s63, s35, 0
	s_add_i32 s64, s57, s91
	global_load_lds_dwordx4 v[190:191], off
	v_lshl_add_u64 v[218:219], s[62:63], 0, v[130:131]
	s_mov_b32 m0, s64
	v_lshl_add_u64 v[220:221], s[36:37], 0, v[132:133]
	global_load_lds_dwordx4 v[218:219], off
	v_lshl_add_u64 v[218:219], s[62:63], 0, v[134:135]
	s_add_i32 m0, s64, 0x2000
	s_nop 0
	global_load_lds_dwordx4 v[218:219], off
	v_lshl_add_u64 v[218:219], s[36:37], 0, v[128:129]
	s_mov_b32 m0, s27
	s_nop 0
	global_load_lds_dwordx4 v[218:219], off
	s_mov_b32 m0, s29
	s_nop 0
	global_load_lds_dwordx4 v[220:221], off
	s_waitcnt vmcnt(8)
	s_waitcnt lgkmcnt(0)
	s_barrier
; #define PG8_STAGE(bufoff, gbase, voff) do { _Pragma("unroll") for (int _i = 0; _i < 2; ++_i) \
;         __builtin_amdgcn_global_load_lds((const unsigned*)((const char*)(gbase) + (voff)[_i]), (LAS unsigned*)(lds + (bufoff) + ldsw + _i * 8192), 16, 0, 0); } while (0)
; #define PG8_LDA(dst, b, h) do { _Pragma("unroll") for (int m = 0; m < 4; ++m) _Pragma("unroll") for (int k = 0; k < 2; ++k) dst[m][k] = *(const LAS bf16x8*)(lds + PG8_SA(b, h) + aoff + m * 2048 + k * 1024); } while (0)
; #define PG8_LDB(dst, b, h) do { _Pragma("unroll") for (int n = 0; n < 2; ++n) _Pragma("unroll") for (int k = 0; k < 2; ++k) dst[n][k] = *(const LAS bf16x8*)(lds + PG8_SB(b, h) + boff + n * 2048 + k * 1024); } while (0)
; #define PG8_MMA(ai, bj, At, Bt) do { __builtin_amdgcn_s_setprio(1); _Pragma("unroll") for (int m = 0; m < 4; ++m) _Pragma("unroll") for (int n = 0; n < 2; ++n) _Pragma("unroll") for (int k = 0; k < 2; ++k) \
;         acc[ai][bj][m][n] = __builtin_amdgcn_mfma_f32_16x16x32_bf16(Bt[n][k], At[m][k], acc[ai][bj][m][n], 0, 0, 0); __builtin_amdgcn_s_setprio(0); } while (0)
; #define PG8_WAIT_V(n) asm volatile("s_waitcnt vmcnt(" #n ")" ::: "memory")
; #define PG8_WAIT_L(n) asm volatile("s_waitcnt lgkmcnt(" #n ")" ::: "memory")
; #define PG8_BAR __builtin_amdgcn_s_barrier()
; #define PG8_SCHED __builtin_amdgcn_sched_barrier(0)
; template <class Epi, class Sched>
; __device__ __forceinline__ void gemm_phase(LAS unsigned char* lds, const Gemm g, const Sched& S, const Epi& E, float* part, int wave) {
;     ...
;             PG8_WAIT_V(8); PG8_WAIT_L(0); PG8_BAR; PG8_MMA(1, 0, At, B0); PG8_MMA(1, 1, At, B1); PG8_BAR; PG8_SCHED;
;             PG8_LDB(B0, 1, 0); PG8_LDB(B1, 1, 1); PG8_SCHED; PG8_LDA(At, 1, 0); PG8_STAGE(PG8_SA(0, 1), a2 + hstep, voffA);
;             PG8_WAIT_V(8); PG8_WAIT_L(0); PG8_BAR; PG8_MMA(0, 0, At, B0); PG8_MMA(0, 1, At, B1); PG8_BAR; PG8_SCHED;
	s_setprio 1
	s_waitcnt lgkmcnt(0)
	v_mfma_f32_16x16x32_bf16 v[60:63], v[142:145], v[182:185], v[60:63]
	v_mfma_f32_16x16x32_bf16 v[56:59], v[158:161], v[182:185], v[56:59]
	v_mfma_f32_16x16x32_bf16 v[44:47], v[142:145], v[194:197], v[44:47]
	v_mfma_f32_16x16x32_bf16 v[40:43], v[158:161], v[194:197], v[40:43]
	v_mfma_f32_16x16x32_bf16 v[28:31], v[142:145], v[202:205], v[28:31]
	v_mfma_f32_16x16x32_bf16 v[24:27], v[158:161], v[202:205], v[24:27]
	v_mfma_f32_16x16x32_bf16 v[12:15], v[142:145], v[210:213], v[12:15]
	v_mfma_f32_16x16x32_bf16 v[8:11], v[158:161], v[210:213], v[8:11]
	v_mfma_f32_16x16x32_bf16 v[60:63], v[154:157], v[186:189], v[60:63]
	v_mfma_f32_16x16x32_bf16 v[56:59], v[162:165], v[186:189], v[56:59]
	v_mfma_f32_16x16x32_bf16 v[44:47], v[154:157], v[198:201], v[44:47]
	v_mfma_f32_16x16x32_bf16 v[40:43], v[162:165], v[198:201], v[40:43]
	v_mfma_f32_16x16x32_bf16 v[28:31], v[154:157], v[206:209], v[28:31]
	v_mfma_f32_16x16x32_bf16 v[24:27], v[162:165], v[206:209], v[24:27]
	v_mfma_f32_16x16x32_bf16 v[12:15], v[154:157], v[214:217], v[12:15]
	v_mfma_f32_16x16x32_bf16 v[8:11], v[162:165], v[214:217], v[8:11]
	s_setprio 0
	s_setprio 1
	v_mfma_f32_16x16x32_bf16 v[52:55], v[166:169], v[182:185], v[52:55]
	v_mfma_f32_16x16x32_bf16 v[48:51], v[174:177], v[182:185], v[48:51]
	v_mfma_f32_16x16x32_bf16 v[36:39], v[166:169], v[194:197], v[36:39]
	v_mfma_f32_16x16x32_bf16 v[32:35], v[174:177], v[194:197], v[32:35]
	v_mfma_f32_16x16x32_bf16 v[20:23], v[166:169], v[202:205], v[20:23]
	v_mfma_f32_16x16x32_bf16 v[16:19], v[174:177], v[202:205], v[16:19]
	v_mfma_f32_16x16x32_bf16 v[4:7], v[166:169], v[210:213], v[4:7]
	v_mfma_f32_16x16x32_bf16 v[0:3], v[174:177], v[210:213], v[0:3]
	v_mfma_f32_16x16x32_bf16 v[52:55], v[170:173], v[186:189], v[52:55]
	v_mfma_f32_16x16x32_bf16 v[48:51], v[178:181], v[186:189], v[48:51]
	v_mfma_f32_16x16x32_bf16 v[36:39], v[170:173], v[198:201], v[36:39]
	v_mfma_f32_16x16x32_bf16 v[32:35], v[178:181], v[198:201], v[32:35]
	v_mfma_f32_16x16x32_bf16 v[20:23], v[170:173], v[206:209], v[20:23]
	v_mfma_f32_16x16x32_bf16 v[16:19], v[178:181], v[206:209], v[16:19]
	v_mfma_f32_16x16x32_bf16 v[4:7], v[170:173], v[214:217], v[4:7]
	v_mfma_f32_16x16x32_bf16 v[0:3], v[178:181], v[214:217], v[0:3]
	s_setprio 0
	s_barrier
	s_add_i32 s62, 0, 0x18000
	s_add_i32 s63, 0, 0x1c000
	v_add_u32_e32 v162, s62, v149
	v_add_u32_e32 v178, s63, v149
	ds_read_b128 v[142:145], v162
	ds_read_b128 v[154:157], v162 offset:1024
	ds_read_b128 v[158:161], v162 offset:2048
	ds_read_b128 v[162:165], v162 offset:3072
	ds_read_b128 v[166:169], v178
	ds_read_b128 v[170:173], v178 offset:1024
	ds_read_b128 v[174:177], v178 offset:2048
	ds_read_b128 v[178:181], v178 offset:3072
	s_add_u32 s36, s36, 0x20000
	s_addc_u32 s37, s37, 0
	s_mov_b32 m0, s41
	v_lshl_add_u64 v[222:223], s[36:37], 0, v[128:129]
	ds_read_b128 v[182:185], v153 offset:32768
	ds_read_b128 v[186:189], v153 offset:33792
	ds_read_b128 v[194:197], v153 offset:34816
	ds_read_b128 v[198:201], v153 offset:35840
	ds_read_b128 v[202:205], v153 offset:36864
	ds_read_b128 v[206:209], v153 offset:37888
	ds_read_b128 v[210:213], v153 offset:38912
	ds_read_b128 v[214:217], v153 offset:39936
	global_load_lds_dwordx4 v[222:223], off
	v_lshl_add_u64 v[222:223], s[36:37], 0, v[132:133]
	s_mov_b32 m0, s50
	s_nop 0
	global_load_lds_dwordx4 v[222:223], off
	s_waitcnt vmcnt(8)
	s_waitcnt lgkmcnt(0)
	s_barrier
	s_setprio 1
	s_waitcnt lgkmcnt(0)
	v_mfma_f32_16x16x32_bf16 v[124:127], v[142:145], v[182:185], v[124:127]
	v_mfma_f32_16x16x32_bf16 v[120:123], v[158:161], v[182:185], v[120:123]
	v_mfma_f32_16x16x32_bf16 v[108:111], v[142:145], v[194:197], v[108:111]
	v_mfma_f32_16x16x32_bf16 v[104:107], v[158:161], v[194:197], v[104:107]
	v_mfma_f32_16x16x32_bf16 v[92:95], v[142:145], v[202:205], v[92:95]
	v_mfma_f32_16x16x32_bf16 v[88:91], v[158:161], v[202:205], v[88:91]
	v_mfma_f32_16x16x32_bf16 v[76:79], v[142:145], v[210:213], v[76:79]
	v_mfma_f32_16x16x32_bf16 v[72:75], v[158:161], v[210:213], v[72:75]
	v_mfma_f32_16x16x32_bf16 v[124:127], v[154:157], v[186:189], v[124:127]
	v_mfma_f32_16x16x32_bf16 v[120:123], v[162:165], v[186:189], v[120:123]
	v_mfma_f32_16x16x32_bf16 v[108:111], v[154:157], v[198:201], v[108:111]
	v_mfma_f32_16x16x32_bf16 v[104:107], v[162:165], v[198:201], v[104:107]
	v_mfma_f32_16x16x32_bf16 v[92:95], v[154:157], v[206:209], v[92:95]
	v_mfma_f32_16x16x32_bf16 v[88:91], v[162:165], v[206:209], v[88:91]
	v_mfma_f32_16x16x32_bf16 v[76:79], v[154:157], v[214:217], v[76:79]
	v_mfma_f32_16x16x32_bf16 v[72:75], v[162:165], v[214:217], v[72:75]
	s_setprio 0
	s_setprio 1
	v_mfma_f32_16x16x32_bf16 v[116:119], v[166:169], v[182:185], v[116:119]
	v_mfma_f32_16x16x32_bf16 v[112:115], v[174:177], v[182:185], v[112:115]
	v_mfma_f32_16x16x32_bf16 v[100:103], v[166:169], v[194:197], v[100:103]
	v_mfma_f32_16x16x32_bf16 v[96:99], v[174:177], v[194:197], v[96:99]
	v_mfma_f32_16x16x32_bf16 v[84:87], v[166:169], v[202:205], v[84:87]
	v_mfma_f32_16x16x32_bf16 v[80:83], v[174:177], v[202:205], v[80:83]
	v_mfma_f32_16x16x32_bf16 v[68:71], v[166:169], v[210:213], v[68:71]
	v_mfma_f32_16x16x32_bf16 v[64:67], v[174:177], v[210:213], v[64:67]
	v_mfma_f32_16x16x32_bf16 v[116:119], v[170:173], v[186:189], v[116:119]
	v_mfma_f32_16x16x32_bf16 v[112:115], v[178:181], v[186:189], v[112:115]
	v_mfma_f32_16x16x32_bf16 v[100:103], v[170:173], v[198:201], v[100:103]
	v_mfma_f32_16x16x32_bf16 v[96:99], v[178:181], v[198:201], v[96:99]
	v_mfma_f32_16x16x32_bf16 v[84:87], v[170:173], v[206:209], v[84:87]
	v_mfma_f32_16x16x32_bf16 v[80:83], v[178:181], v[206:209], v[80:83]
	v_mfma_f32_16x16x32_bf16 v[68:71], v[170:173], v[214:217], v[68:71]
	v_mfma_f32_16x16x32_bf16 v[64:67], v[178:181], v[214:217], v[64:67]
	s_setprio 0
	s_barrier
; #define PG8_STAGE(bufoff, gbase, voff) do { _Pragma("unroll") for (int _i = 0; _i < 2; ++_i) \
;         __builtin_amdgcn_global_load_lds((const unsigned*)((const char*)(gbase) + (voff)[_i]), (LAS unsigned*)(lds + (bufoff) + ldsw + _i * 8192), 16, 0, 0); } while (0)
; #define PG8_LDA(dst, b, h) do { _Pragma("unroll") for (int m = 0; m < 4; ++m) _Pragma("unroll") for (int k = 0; k < 2; ++k) dst[m][k] = *(const LAS bf16x8*)(lds + PG8_SA(b, h) + aoff + m * 2048 + k * 1024); } while (0)
; #define PG8_MMA(ai, bj, At, Bt) do { __builtin_amdgcn_s_setprio(1); _Pragma("unroll") for (int m = 0; m < 4; ++m) _Pragma("unroll") for (int n = 0; n < 2; ++n) _Pragma("unroll") for (int k = 0; k < 2; ++k) \
;         acc[ai][bj][m][n] = __builtin_amdgcn_mfma_f32_16x16x32_bf16(Bt[n][k], At[m][k], acc[ai][bj][m][n], 0, 0, 0); __builtin_amdgcn_s_setprio(0); } while (0)
; #define PG8_WAIT_V(n) asm volatile("s_waitcnt vmcnt(" #n ")" ::: "memory")
; #define PG8_WAIT_L(n) asm volatile("s_waitcnt lgkmcnt(" #n ")" ::: "memory")
; #define PG8_BAR __builtin_amdgcn_s_barrier()
; #define PG8_SCHED __builtin_amdgcn_sched_barrier(0)
; template <class Epi, class Sched>
; __device__ __forceinline__ void gemm_phase(LAS unsigned char* lds, const Gemm g, const Sched& S, const Epi& E, float* part, int wave) {
;     ...
;             PG8_LDA(At, 1, 1); PG8_STAGE(PG8_SB(1, 0), b3, voffB); PG8_STAGE(PG8_SB(1, 1), b3 + hstep, voffB); PG8_STAGE(PG8_SA(1, 0), a3, voffA);
;             PG8_WAIT_V(8); PG8_WAIT_L(0); PG8_BAR; PG8_MMA(1, 0, At, B0); PG8_MMA(1, 1, At, B1); PG8_BAR; PG8_SCHED;
;         }
;         if (wr == 0) PG8_BAR;
	s_add_i32 s36, s62, s91
	v_lshl_add_u64 v[146:147], v[146:147], 0, s[12:13]
	s_mov_b32 m0, s36
	ds_read_b128 v[182:185], v153 offset:49152
	ds_read_b128 v[186:189], v153 offset:50176
	ds_read_b128 v[194:197], v153 offset:51200
	ds_read_b128 v[198:201], v153 offset:52224
	ds_read_b128 v[202:205], v153 offset:53248
	ds_read_b128 v[206:209], v153 offset:54272
	ds_read_b128 v[210:213], v153 offset:55296
	ds_read_b128 v[214:217], v153 offset:56320
	global_load_lds_dwordx4 v[146:147], off
	s_add_i32 m0, s36, 0x2000
	s_add_u32 s34, s34, 0x20080
	v_lshl_add_u64 v[146:147], v[190:191], 0, s[12:13]
	s_addc_u32 s35, s35, 0
	s_add_i32 s36, s63, s91
	global_load_lds_dwordx4 v[146:147], off
	v_lshl_add_u64 v[146:147], s[34:35], 0, v[130:131]
	s_mov_b32 m0, s36
	s_nop 0
	global_load_lds_dwordx4 v[146:147], off
	v_lshl_add_u64 v[146:147], s[34:35], 0, v[134:135]
	s_add_i32 m0, s36, 0x2000
	s_nop 0
	global_load_lds_dwordx4 v[146:147], off
	v_lshl_add_u64 v[146:147], v[218:219], 0, s[12:13]
	s_mov_b32 m0, s52
	s_nop 0
	global_load_lds_dwordx4 v[146:147], off
	v_lshl_add_u64 v[146:147], v[220:221], 0, s[12:13]
	s_mov_b32 m0, s53
	s_nop 0
	global_load_lds_dwordx4 v[146:147], off
	s_waitcnt vmcnt(8)
	s_waitcnt lgkmcnt(0)
	s_barrier
	s_setprio 1
	s_waitcnt lgkmcnt(0)
	v_mfma_f32_16x16x32_bf16 v[60:63], v[142:145], v[182:185], v[60:63]
	v_mfma_f32_16x16x32_bf16 v[56:59], v[158:161], v[182:185], v[56:59]
	v_mfma_f32_16x16x32_bf16 v[44:47], v[142:145], v[194:197], v[44:47]
	v_mfma_f32_16x16x32_bf16 v[40:43], v[158:161], v[194:197], v[40:43]
	v_mfma_f32_16x16x32_bf16 v[28:31], v[142:145], v[202:205], v[28:31]
	v_mfma_f32_16x16x32_bf16 v[24:27], v[158:161], v[202:205], v[24:27]
	v_mfma_f32_16x16x32_bf16 v[12:15], v[142:145], v[210:213], v[12:15]
	v_mfma_f32_16x16x32_bf16 v[8:11], v[158:161], v[210:213], v[8:11]
	v_mfma_f32_16x16x32_bf16 v[60:63], v[154:157], v[186:189], v[60:63]
	v_mfma_f32_16x16x32_bf16 v[56:59], v[162:165], v[186:189], v[56:59]
	v_mfma_f32_16x16x32_bf16 v[44:47], v[154:157], v[198:201], v[44:47]
	v_mfma_f32_16x16x32_bf16 v[40:43], v[162:165], v[198:201], v[40:43]
	v_mfma_f32_16x16x32_bf16 v[28:31], v[154:157], v[206:209], v[28:31]
	v_mfma_f32_16x16x32_bf16 v[24:27], v[162:165], v[206:209], v[24:27]
	v_mfma_f32_16x16x32_bf16 v[12:15], v[154:157], v[214:217], v[12:15]
	v_mfma_f32_16x16x32_bf16 v[8:11], v[162:165], v[214:217], v[8:11]
	s_setprio 0
	s_setprio 1
	v_mfma_f32_16x16x32_bf16 v[52:55], v[166:169], v[182:185], v[52:55]
	v_mfma_f32_16x16x32_bf16 v[48:51], v[174:177], v[182:185], v[48:51]
	v_mfma_f32_16x16x32_bf16 v[36:39], v[166:169], v[194:197], v[36:39]
	v_mfma_f32_16x16x32_bf16 v[32:35], v[174:177], v[194:197], v[32:35]
	v_mfma_f32_16x16x32_bf16 v[20:23], v[166:169], v[202:205], v[20:23]
	v_mfma_f32_16x16x32_bf16 v[16:19], v[174:177], v[202:205], v[16:19]
	v_mfma_f32_16x16x32_bf16 v[4:7], v[166:169], v[210:213], v[4:7]
	v_mfma_f32_16x16x32_bf16 v[0:3], v[174:177], v[210:213], v[0:3]
	v_mfma_f32_16x16x32_bf16 v[52:55], v[170:173], v[186:189], v[52:55]
	v_mfma_f32_16x16x32_bf16 v[48:51], v[178:181], v[186:189], v[48:51]
	v_mfma_f32_16x16x32_bf16 v[36:39], v[170:173], v[198:201], v[36:39]
	v_mfma_f32_16x16x32_bf16 v[32:35], v[178:181], v[198:201], v[32:35]
	v_mfma_f32_16x16x32_bf16 v[20:23], v[170:173], v[206:209], v[20:23]
	v_mfma_f32_16x16x32_bf16 v[16:19], v[178:181], v[206:209], v[16:19]
	v_mfma_f32_16x16x32_bf16 v[4:7], v[170:173], v[214:217], v[4:7]
	v_mfma_f32_16x16x32_bf16 v[0:3], v[178:181], v[214:217], v[0:3]
	s_add_i32 s59, s59, 2
	s_add_u32 s19, s19, 0x100
	s_addc_u32 s21, s21, 0
	s_add_u32 s30, s30, 0x100
	s_addc_u32 s31, s31, 0
	s_cmp_gt_u32 s59, 5
	s_setprio 0
	s_barrier
	s_cbranch_scc0 .LBB0_825
	s_and_b64 vcc, exec, s[48:49]
	s_cbranch_vccz .LBB0_828
	s_barrier

; #define PG8_STAGE(bufoff, gbase, voff) do { _Pragma("unroll") for (int _i = 0; _i < 2; ++_i) \
;         __builtin_amdgcn_global_load_lds((const unsigned*)((const char*)(gbase) + (voff)[_i]), (LAS unsigned*)(lds + (bufoff) + ldsw + _i * 8192), 16, 0, 0); } while (0)
; #define PG8_LDA(dst, b, h) do { _Pragma("unroll") for (int m = 0; m < 4; ++m) _Pragma("unroll") for (int k = 0; k < 2; ++k) dst[m][k] = *(const LAS bf16x8*)(lds + PG8_SA(b, h) + aoff + m * 2048 + k * 1024); } while (0)
; #define PG8_LDB(dst, b, h) do { _Pragma("unroll") for (int n = 0; n < 2; ++n) _Pragma("unroll") for (int k = 0; k < 2; ++k) dst[n][k] = *(const LAS bf16x8*)(lds + PG8_SB(b, h) + boff + n * 2048 + k * 1024); } while (0)
; #define PG8_MMA(ai, bj, At, Bt) do { __builtin_amdgcn_s_setprio(1); _Pragma("unroll") for (int m = 0; m < 4; ++m) _Pragma("unroll") for (int n = 0; n < 2; ++n) _Pragma("unroll") for (int k = 0; k < 2; ++k) \
;         acc[ai][bj][m][n] = __builtin_amdgcn_mfma_f32_16x16x32_bf16(Bt[n][k], At[m][k], acc[ai][bj][m][n], 0, 0, 0); __builtin_amdgcn_s_setprio(0); } while (0)
; #define PG8_WAIT_V(n) asm volatile("s_waitcnt vmcnt(" #n ")" ::: "memory")
; #define PG8_WAIT_L(n) asm volatile("s_waitcnt lgkmcnt(" #n ")" ::: "memory")
; #define PG8_BAR __builtin_amdgcn_s_barrier()
; #define PG8_SCHED __builtin_amdgcn_sched_barrier(0)
; template <class Epi, class Sched>
; __device__ __forceinline__ void gemm_phase(LAS unsigned char* lds, const Gemm g, const Sched& S, const Epi& E, float* part, int wave) {
;     ...
;         for (int t = 0; t < nt; t += 2) {
;             const bool last = (t == nt - 2);
;             const char* a1 = cA + (size_t)(t + 1) * kstep;
;             const char* a2 = last ? nA : cA + (size_t)(t + 2) * kstep; const char* b2 = last ? nB : cB + (size_t)(t + 2) * kstep;
;             const char* a3 = a2 + kstep; const char* b3 = b2 + kstep;
;             PG8_LDB(B0, 0, 0); PG8_LDB(B1, 0, 1); PG8_SCHED; PG8_LDA(At, 0, 0); PG8_STAGE(PG8_SA(1, 1), a1 + hstep, voffA);
;             PG8_WAIT_V(8); PG8_WAIT_L(0); PG8_BAR; PG8_MMA(0, 0, At, B0); PG8_MMA(0, 1, At, B1); PG8_BAR; PG8_SCHED;
;             PG8_LDA(At, 0, 1); PG8_STAGE(PG8_SB(0, 0), b2, voffB); PG8_STAGE(PG8_SB(0, 1), b2 + hstep, voffB); PG8_STAGE(PG8_SA(0, 0), a2, voffA);
;             PG8_WAIT_V(8); PG8_WAIT_L(0); PG8_BAR; PG8_MMA(1, 0, At, B0); PG8_MMA(1, 1, At, B1); PG8_BAR; PG8_SCHED;
.LBB0_905:
	ds_read_b128 v[140:143], v147
	ds_read_b128 v[150:153], v147 offset:1024
	ds_read_b128 v[154:157], v147 offset:2048
	ds_read_b128 v[158:161], v147 offset:3072
	ds_read_b128 v[162:165], v148
	ds_read_b128 v[166:169], v148 offset:1024
	ds_read_b128 v[170:173], v148 offset:2048
	ds_read_b128 v[174:177], v148 offset:3072
	s_add_i32 s88, s64, 2
	s_add_u32 s36, s34, 0x100
	s_addc_u32 s37, s35, 0
	s_cmp_eq_u32 s21, s64
	s_cselect_b32 s64, s26, s23
	s_cselect_b32 s67, s25, s37
	s_cselect_b32 s66, s24, s36
	s_cselect_b32 s65, s27, s87
	v_lshl_add_u64 v[190:191], s[34:35], 0, v[136:137]
	s_add_i32 m0, s5, 0xc000
	ds_read_b128 v[178:181], v149
	ds_read_b128 v[182:185], v149 offset:1024
	ds_read_b128 v[186:189], v149 offset:2048
	ds_read_b128 v[194:197], v149 offset:3072
	ds_read_b128 v[198:201], v149 offset:4096
	ds_read_b128 v[202:205], v149 offset:5120
	ds_read_b128 v[206:209], v149 offset:6144
	ds_read_b128 v[210:213], v149 offset:7168
	global_load_lds_dwordx4 v[190:191], off
	v_lshl_add_u64 v[190:191], s[34:35], 0, v[134:135]
	s_add_i32 m0, s5, 0xe000
	s_nop 0
	global_load_lds_dwordx4 v[190:191], off
	s_waitcnt vmcnt(8)
	s_waitcnt lgkmcnt(0)
	s_barrier
	s_setprio 1
	s_waitcnt lgkmcnt(0)
	v_mfma_f32_16x16x32_bf16 v[124:127], v[140:143], v[178:181], v[124:127]
	v_mfma_f32_16x16x32_bf16 v[120:123], v[154:157], v[178:181], v[120:123]
	v_mfma_f32_16x16x32_bf16 v[116:119], v[140:143], v[186:189], v[116:119]
	v_mfma_f32_16x16x32_bf16 v[112:115], v[154:157], v[186:189], v[112:115]
	v_mfma_f32_16x16x32_bf16 v[108:111], v[140:143], v[198:201], v[108:111]
	v_mfma_f32_16x16x32_bf16 v[104:107], v[154:157], v[198:201], v[104:107]
	v_mfma_f32_16x16x32_bf16 v[100:103], v[140:143], v[206:209], v[100:103]
	v_mfma_f32_16x16x32_bf16 v[96:99], v[154:157], v[206:209], v[96:99]
	v_mfma_f32_16x16x32_bf16 v[124:127], v[150:153], v[182:185], v[124:127]
	v_mfma_f32_16x16x32_bf16 v[120:123], v[158:161], v[182:185], v[120:123]
	v_mfma_f32_16x16x32_bf16 v[116:119], v[150:153], v[194:197], v[116:119]
	v_mfma_f32_16x16x32_bf16 v[112:115], v[158:161], v[194:197], v[112:115]
	v_mfma_f32_16x16x32_bf16 v[108:111], v[150:153], v[202:205], v[108:111]
	v_mfma_f32_16x16x32_bf16 v[104:107], v[158:161], v[202:205], v[104:107]
	v_mfma_f32_16x16x32_bf16 v[100:103], v[150:153], v[210:213], v[100:103]
	v_mfma_f32_16x16x32_bf16 v[96:99], v[158:161], v[210:213], v[96:99]
	s_setprio 0
	s_setprio 1
	v_mfma_f32_16x16x32_bf16 v[92:95], v[162:165], v[178:181], v[92:95]
	v_mfma_f32_16x16x32_bf16 v[88:91], v[170:173], v[178:181], v[88:91]
	v_mfma_f32_16x16x32_bf16 v[84:87], v[162:165], v[186:189], v[84:87]
	v_mfma_f32_16x16x32_bf16 v[80:83], v[170:173], v[186:189], v[80:83]
	v_mfma_f32_16x16x32_bf16 v[76:79], v[162:165], v[198:201], v[76:79]
	v_mfma_f32_16x16x32_bf16 v[72:75], v[170:173], v[198:201], v[72:75]
	v_mfma_f32_16x16x32_bf16 v[68:71], v[162:165], v[206:209], v[68:71]
	v_mfma_f32_16x16x32_bf16 v[64:67], v[170:173], v[206:209], v[64:67]
	v_mfma_f32_16x16x32_bf16 v[92:95], v[166:169], v[182:185], v[92:95]
	v_mfma_f32_16x16x32_bf16 v[88:91], v[174:177], v[182:185], v[88:91]
	v_mfma_f32_16x16x32_bf16 v[84:87], v[166:169], v[194:197], v[84:87]
	v_mfma_f32_16x16x32_bf16 v[80:83], v[174:177], v[194:197], v[80:83]
	v_mfma_f32_16x16x32_bf16 v[76:79], v[166:169], v[202:205], v[76:79]
	v_mfma_f32_16x16x32_bf16 v[72:75], v[174:177], v[202:205], v[72:75]
	v_mfma_f32_16x16x32_bf16 v[68:71], v[166:169], v[210:213], v[68:71]
	v_mfma_f32_16x16x32_bf16 v[64:67], v[174:177], v[210:213], v[64:67]
	s_setprio 0
	s_barrier
	s_add_i32 s34, s76, s91
	v_lshl_add_u64 v[190:191], s[64:65], 0, v[128:129]
	s_mov_b32 m0, s34
	ds_read_b128 v[178:181], v149 offset:16384
	ds_read_b128 v[182:185], v149 offset:17408
	ds_read_b128 v[186:189], v149 offset:18432
	ds_read_b128 v[194:197], v149 offset:19456
	ds_read_b128 v[198:201], v149 offset:20480
	ds_read_b128 v[202:205], v149 offset:21504
	ds_read_b128 v[206:209], v149 offset:22528
	ds_read_b128 v[210:213], v149 offset:23552
	global_load_lds_dwordx4 v[190:191], off
	s_add_i32 m0, s34, 0x2000
	s_add_u32 s34, s64, 0x100000
	v_lshl_add_u64 v[214:215], s[64:65], 0, v[130:131]
	s_addc_u32 s35, s65, 0
	s_add_i32 s89, s77, s91
	global_load_lds_dwordx4 v[214:215], off
	v_lshl_add_u64 v[216:217], s[34:35], 0, v[128:129]
	s_mov_b32 m0, s89
	v_lshl_add_u64 v[218:219], s[66:67], 0, v[130:131]
	global_load_lds_dwordx4 v[216:217], off
	v_lshl_add_u64 v[216:217], s[34:35], 0, v[130:131]
	s_add_i32 m0, s89, 0x2000
	s_nop 0
	global_load_lds_dwordx4 v[216:217], off
	v_lshl_add_u64 v[216:217], s[66:67], 0, v[128:129]
	s_mov_b32 m0, s5
	s_nop 0
	global_load_lds_dwordx4 v[216:217], off
	s_mov_b32 m0, s17
	s_nop 0
	global_load_lds_dwordx4 v[218:219], off
	s_waitcnt vmcnt(8)
	s_waitcnt lgkmcnt(0)
	s_barrier
; #define PG8_STAGE(bufoff, gbase, voff) do { _Pragma("unroll") for (int _i = 0; _i < 2; ++_i) \
;         __builtin_amdgcn_global_load_lds((const unsigned*)((const char*)(gbase) + (voff)[_i]), (LAS unsigned*)(lds + (bufoff) + ldsw + _i * 8192), 16, 0, 0); } while (0)
; #define PG8_LDA(dst, b, h) do { _Pragma("unroll") for (int m = 0; m < 4; ++m) _Pragma("unroll") for (int k = 0; k < 2; ++k) dst[m][k] = *(const LAS bf16x8*)(lds + PG8_SA(b, h) + aoff + m * 2048 + k * 1024); } while (0)
; #define PG8_LDB(dst, b, h) do { _Pragma("unroll") for (int n = 0; n < 2; ++n) _Pragma("unroll") for (int k = 0; k < 2; ++k) dst[n][k] = *(const LAS bf16x8*)(lds + PG8_SB(b, h) + boff + n * 2048 + k * 1024); } while (0)
; #define PG8_MMA(ai, bj, At, Bt) do { __builtin_amdgcn_s_setprio(1); _Pragma("unroll") for (int m = 0; m < 4; ++m) _Pragma("unroll") for (int n = 0; n < 2; ++n) _Pragma("unroll") for (int k = 0; k < 2; ++k) \
;         acc[ai][bj][m][n] = __builtin_amdgcn_mfma_f32_16x16x32_bf16(Bt[n][k], At[m][k], acc[ai][bj][m][n], 0, 0, 0); __builtin_amdgcn_s_setprio(0); } while (0)
; #define PG8_WAIT_V(n) asm volatile("s_waitcnt vmcnt(" #n ")" ::: "memory")
; #define PG8_WAIT_L(n) asm volatile("s_waitcnt lgkmcnt(" #n ")" ::: "memory")
; #define PG8_BAR __builtin_amdgcn_s_barrier()
; #define PG8_SCHED __builtin_amdgcn_sched_barrier(0)
; template <class Epi, class Sched>
; __device__ __forceinline__ void gemm_phase(LAS unsigned char* lds, const Gemm g, const Sched& S, const Epi& E, float* part, int wave) {
;     ...
;             PG8_WAIT_V(8); PG8_WAIT_L(0); PG8_BAR; PG8_MMA(1, 0, At, B0); PG8_MMA(1, 1, At, B1); PG8_BAR; PG8_SCHED;
;             PG8_LDB(B0, 1, 0); PG8_LDB(B1, 1, 1); PG8_SCHED; PG8_LDA(At, 1, 0); PG8_STAGE(PG8_SA(0, 1), a2 + hstep, voffA);
;             PG8_WAIT_V(8); PG8_WAIT_L(0); PG8_BAR; PG8_MMA(0, 0, At, B0); PG8_MMA(0, 1, At, B1); PG8_BAR; PG8_SCHED;
	s_setprio 1
	s_waitcnt lgkmcnt(0)
	v_mfma_f32_16x16x32_bf16 v[60:63], v[140:143], v[178:181], v[60:63]
	v_mfma_f32_16x16x32_bf16 v[56:59], v[154:157], v[178:181], v[56:59]
	v_mfma_f32_16x16x32_bf16 v[52:55], v[140:143], v[186:189], v[52:55]
	v_mfma_f32_16x16x32_bf16 v[48:51], v[154:157], v[186:189], v[48:51]
	v_mfma_f32_16x16x32_bf16 v[44:47], v[140:143], v[198:201], v[44:47]
	v_mfma_f32_16x16x32_bf16 v[40:43], v[154:157], v[198:201], v[40:43]
	v_mfma_f32_16x16x32_bf16 v[36:39], v[140:143], v[206:209], v[36:39]
	v_mfma_f32_16x16x32_bf16 v[32:35], v[154:157], v[206:209], v[32:35]
	v_mfma_f32_16x16x32_bf16 v[60:63], v[150:153], v[182:185], v[60:63]
	v_mfma_f32_16x16x32_bf16 v[56:59], v[158:161], v[182:185], v[56:59]
	v_mfma_f32_16x16x32_bf16 v[52:55], v[150:153], v[194:197], v[52:55]
	v_mfma_f32_16x16x32_bf16 v[48:51], v[158:161], v[194:197], v[48:51]
	v_mfma_f32_16x16x32_bf16 v[44:47], v[150:153], v[202:205], v[44:47]
	v_mfma_f32_16x16x32_bf16 v[40:43], v[158:161], v[202:205], v[40:43]
	v_mfma_f32_16x16x32_bf16 v[36:39], v[150:153], v[210:213], v[36:39]
	v_mfma_f32_16x16x32_bf16 v[32:35], v[158:161], v[210:213], v[32:35]
	s_setprio 0
	s_setprio 1
	v_mfma_f32_16x16x32_bf16 v[28:31], v[162:165], v[178:181], v[28:31]
	v_mfma_f32_16x16x32_bf16 v[24:27], v[170:173], v[178:181], v[24:27]
	v_mfma_f32_16x16x32_bf16 v[20:23], v[162:165], v[186:189], v[20:23]
	v_mfma_f32_16x16x32_bf16 v[16:19], v[170:173], v[186:189], v[16:19]
	v_mfma_f32_16x16x32_bf16 v[12:15], v[162:165], v[198:201], v[12:15]
	v_mfma_f32_16x16x32_bf16 v[8:11], v[170:173], v[198:201], v[8:11]
	v_mfma_f32_16x16x32_bf16 v[4:7], v[162:165], v[206:209], v[4:7]
	v_mfma_f32_16x16x32_bf16 v[0:3], v[170:173], v[206:209], v[0:3]
	v_mfma_f32_16x16x32_bf16 v[28:31], v[166:169], v[182:185], v[28:31]
	v_mfma_f32_16x16x32_bf16 v[24:27], v[174:177], v[182:185], v[24:27]
	v_mfma_f32_16x16x32_bf16 v[20:23], v[166:169], v[194:197], v[20:23]
	v_mfma_f32_16x16x32_bf16 v[16:19], v[174:177], v[194:197], v[16:19]
	v_mfma_f32_16x16x32_bf16 v[12:15], v[166:169], v[202:205], v[12:15]
	v_mfma_f32_16x16x32_bf16 v[8:11], v[174:177], v[202:205], v[8:11]
	v_mfma_f32_16x16x32_bf16 v[4:7], v[166:169], v[210:213], v[4:7]
	v_mfma_f32_16x16x32_bf16 v[0:3], v[174:177], v[210:213], v[0:3]
	s_setprio 0
	s_barrier
	s_add_i32 s89, 0, 0x18000
	s_add_i32 s90, 0, 0x1c000
	v_add_u32_e32 v158, s89, v145
	v_add_u32_e32 v174, s90, v145
	ds_read_b128 v[140:143], v158
	ds_read_b128 v[150:153], v158 offset:1024
	ds_read_b128 v[154:157], v158 offset:2048
	ds_read_b128 v[158:161], v158 offset:3072
	ds_read_b128 v[162:165], v174
	ds_read_b128 v[166:169], v174 offset:1024
	ds_read_b128 v[170:173], v174 offset:2048
	ds_read_b128 v[174:177], v174 offset:3072
	s_add_u32 s34, s66, 0x100000
	s_addc_u32 s35, s67, 0
	s_mov_b32 m0, s29
	v_lshl_add_u64 v[220:221], s[34:35], 0, v[128:129]
	ds_read_b128 v[178:181], v149 offset:32768
	ds_read_b128 v[182:185], v149 offset:33792
	ds_read_b128 v[186:189], v149 offset:34816
	ds_read_b128 v[194:197], v149 offset:35840
	ds_read_b128 v[198:201], v149 offset:36864
	ds_read_b128 v[202:205], v149 offset:37888
	ds_read_b128 v[206:209], v149 offset:38912
	ds_read_b128 v[210:213], v149 offset:39936
	global_load_lds_dwordx4 v[220:221], off
	v_lshl_add_u64 v[220:221], s[34:35], 0, v[130:131]
	s_mov_b32 m0, s31
	s_nop 0
	global_load_lds_dwordx4 v[220:221], off
	s_waitcnt vmcnt(8)
	s_waitcnt lgkmcnt(0)
	s_barrier
	s_setprio 1
	s_waitcnt lgkmcnt(0)
	v_mfma_f32_16x16x32_bf16 v[124:127], v[140:143], v[178:181], v[124:127]
	v_mfma_f32_16x16x32_bf16 v[120:123], v[154:157], v[178:181], v[120:123]
	v_mfma_f32_16x16x32_bf16 v[116:119], v[140:143], v[186:189], v[116:119]
	v_mfma_f32_16x16x32_bf16 v[112:115], v[154:157], v[186:189], v[112:115]
	v_mfma_f32_16x16x32_bf16 v[108:111], v[140:143], v[198:201], v[108:111]
	v_mfma_f32_16x16x32_bf16 v[104:107], v[154:157], v[198:201], v[104:107]
	v_mfma_f32_16x16x32_bf16 v[100:103], v[140:143], v[206:209], v[100:103]
	v_mfma_f32_16x16x32_bf16 v[96:99], v[154:157], v[206:209], v[96:99]
	v_mfma_f32_16x16x32_bf16 v[124:127], v[150:153], v[182:185], v[124:127]
	v_mfma_f32_16x16x32_bf16 v[120:123], v[158:161], v[182:185], v[120:123]
	v_mfma_f32_16x16x32_bf16 v[116:119], v[150:153], v[194:197], v[116:119]
	v_mfma_f32_16x16x32_bf16 v[112:115], v[158:161], v[194:197], v[112:115]
	v_mfma_f32_16x16x32_bf16 v[108:111], v[150:153], v[202:205], v[108:111]
	v_mfma_f32_16x16x32_bf16 v[104:107], v[158:161], v[202:205], v[104:107]
	v_mfma_f32_16x16x32_bf16 v[100:103], v[150:153], v[210:213], v[100:103]
	v_mfma_f32_16x16x32_bf16 v[96:99], v[158:161], v[210:213], v[96:99]
	s_setprio 0
	s_setprio 1
	v_mfma_f32_16x16x32_bf16 v[92:95], v[162:165], v[178:181], v[92:95]
	v_mfma_f32_16x16x32_bf16 v[88:91], v[170:173], v[178:181], v[88:91]
	v_mfma_f32_16x16x32_bf16 v[84:87], v[162:165], v[186:189], v[84:87]
	v_mfma_f32_16x16x32_bf16 v[80:83], v[170:173], v[186:189], v[80:83]
	v_mfma_f32_16x16x32_bf16 v[76:79], v[162:165], v[198:201], v[76:79]
	v_mfma_f32_16x16x32_bf16 v[72:75], v[170:173], v[198:201], v[72:75]
	v_mfma_f32_16x16x32_bf16 v[68:71], v[162:165], v[206:209], v[68:71]
	v_mfma_f32_16x16x32_bf16 v[64:67], v[170:173], v[206:209], v[64:67]
	v_mfma_f32_16x16x32_bf16 v[92:95], v[166:169], v[182:185], v[92:95]
	v_mfma_f32_16x16x32_bf16 v[88:91], v[174:177], v[182:185], v[88:91]
	v_mfma_f32_16x16x32_bf16 v[84:87], v[166:169], v[194:197], v[84:87]
	v_mfma_f32_16x16x32_bf16 v[80:83], v[174:177], v[194:197], v[80:83]
	v_mfma_f32_16x16x32_bf16 v[76:79], v[166:169], v[202:205], v[76:79]
	v_mfma_f32_16x16x32_bf16 v[72:75], v[174:177], v[202:205], v[72:75]
	v_mfma_f32_16x16x32_bf16 v[68:71], v[166:169], v[210:213], v[68:71]
	v_mfma_f32_16x16x32_bf16 v[64:67], v[174:177], v[210:213], v[64:67]
	s_setprio 0
	s_barrier
; #define PG8_STAGE(bufoff, gbase, voff) do { _Pragma("unroll") for (int _i = 0; _i < 2; ++_i) \
;         __builtin_amdgcn_global_load_lds((const unsigned*)((const char*)(gbase) + (voff)[_i]), (LAS unsigned*)(lds + (bufoff) + ldsw + _i * 8192), 16, 0, 0); } while (0)
; #define PG8_LDA(dst, b, h) do { _Pragma("unroll") for (int m = 0; m < 4; ++m) _Pragma("unroll") for (int k = 0; k < 2; ++k) dst[m][k] = *(const LAS bf16x8*)(lds + PG8_SA(b, h) + aoff + m * 2048 + k * 1024); } while (0)
; #define PG8_MMA(ai, bj, At, Bt) do { __builtin_amdgcn_s_setprio(1); _Pragma("unroll") for (int m = 0; m < 4; ++m) _Pragma("unroll") for (int n = 0; n < 2; ++n) _Pragma("unroll") for (int k = 0; k < 2; ++k) \
;         acc[ai][bj][m][n] = __builtin_amdgcn_mfma_f32_16x16x32_bf16(Bt[n][k], At[m][k], acc[ai][bj][m][n], 0, 0, 0); __builtin_amdgcn_s_setprio(0); } while (0)
; #define PG8_WAIT_V(n) asm volatile("s_waitcnt vmcnt(" #n ")" ::: "memory")
; #define PG8_WAIT_L(n) asm volatile("s_waitcnt lgkmcnt(" #n ")" ::: "memory")
; #define PG8_BAR __builtin_amdgcn_s_barrier()
; #define PG8_SCHED __builtin_amdgcn_sched_barrier(0)
; template <class Epi, class Sched>
; __device__ __forceinline__ void gemm_phase(LAS unsigned char* lds, const Gemm g, const Sched& S, const Epi& E, float* part, int wave) {
;     ...
;             PG8_LDA(At, 1, 1); PG8_STAGE(PG8_SB(1, 0), b3, voffB); PG8_STAGE(PG8_SB(1, 1), b3 + hstep, voffB); PG8_STAGE(PG8_SA(1, 0), a3, voffA);
;             PG8_WAIT_V(8); PG8_WAIT_L(0); PG8_BAR; PG8_MMA(1, 0, At, B0); PG8_MMA(1, 1, At, B1); PG8_BAR; PG8_SCHED;
;         }
	s_add_i32 s34, s89, s91
	v_lshl_add_u64 v[190:191], v[190:191], 0, s[12:13]
	s_mov_b32 m0, s34
	ds_read_b128 v[178:181], v149 offset:49152
	ds_read_b128 v[182:185], v149 offset:50176
	ds_read_b128 v[186:189], v149 offset:51200
	ds_read_b128 v[194:197], v149 offset:52224
	ds_read_b128 v[198:201], v149 offset:53248
	ds_read_b128 v[202:205], v149 offset:54272
	ds_read_b128 v[206:209], v149 offset:55296
	ds_read_b128 v[210:213], v149 offset:56320
	global_load_lds_dwordx4 v[190:191], off
	s_add_i32 m0, s34, 0x2000
	s_add_u32 s34, s64, 0x100080
	v_lshl_add_u64 v[190:191], v[214:215], 0, s[12:13]
	s_addc_u32 s35, s65, 0
	s_add_i32 s64, s90, s91
	global_load_lds_dwordx4 v[190:191], off
	v_lshl_add_u64 v[190:191], s[34:35], 0, v[128:129]
	s_mov_b32 m0, s64
	s_nop 0
	global_load_lds_dwordx4 v[190:191], off
	v_lshl_add_u64 v[190:191], s[34:35], 0, v[130:131]
	s_add_i32 m0, s64, 0x2000
	s_nop 0
	global_load_lds_dwordx4 v[190:191], off
	v_lshl_add_u64 v[190:191], v[216:217], 0, s[12:13]
	s_mov_b32 m0, s33
	s_nop 0
	global_load_lds_dwordx4 v[190:191], off
	v_lshl_add_u64 v[190:191], v[218:219], 0, s[12:13]
	s_mov_b32 m0, s39
	s_nop 0
	global_load_lds_dwordx4 v[190:191], off
	s_waitcnt vmcnt(8)
	s_waitcnt lgkmcnt(0)
	s_barrier
	s_setprio 1
	s_waitcnt lgkmcnt(0)
	v_mfma_f32_16x16x32_bf16 v[60:63], v[140:143], v[178:181], v[60:63]
	v_mfma_f32_16x16x32_bf16 v[56:59], v[154:157], v[178:181], v[56:59]
	v_mfma_f32_16x16x32_bf16 v[52:55], v[140:143], v[186:189], v[52:55]
	v_mfma_f32_16x16x32_bf16 v[48:51], v[154:157], v[186:189], v[48:51]
	v_mfma_f32_16x16x32_bf16 v[44:47], v[140:143], v[198:201], v[44:47]
	v_mfma_f32_16x16x32_bf16 v[40:43], v[154:157], v[198:201], v[40:43]
	v_mfma_f32_16x16x32_bf16 v[36:39], v[140:143], v[206:209], v[36:39]
	v_mfma_f32_16x16x32_bf16 v[32:35], v[154:157], v[206:209], v[32:35]
	v_mfma_f32_16x16x32_bf16 v[60:63], v[150:153], v[182:185], v[60:63]
	v_mfma_f32_16x16x32_bf16 v[56:59], v[158:161], v[182:185], v[56:59]
	v_mfma_f32_16x16x32_bf16 v[52:55], v[150:153], v[194:197], v[52:55]
	v_mfma_f32_16x16x32_bf16 v[48:51], v[158:161], v[194:197], v[48:51]
	v_mfma_f32_16x16x32_bf16 v[44:47], v[150:153], v[202:205], v[44:47]
	v_mfma_f32_16x16x32_bf16 v[40:43], v[158:161], v[202:205], v[40:43]
	v_mfma_f32_16x16x32_bf16 v[36:39], v[150:153], v[210:213], v[36:39]
	v_mfma_f32_16x16x32_bf16 v[32:35], v[158:161], v[210:213], v[32:35]
	s_setprio 0
	s_setprio 1
	v_mfma_f32_16x16x32_bf16 v[28:31], v[162:165], v[178:181], v[28:31]
	v_mfma_f32_16x16x32_bf16 v[24:27], v[170:173], v[178:181], v[24:27]
	v_mfma_f32_16x16x32_bf16 v[20:23], v[162:165], v[186:189], v[20:23]
	v_mfma_f32_16x16x32_bf16 v[16:19], v[170:173], v[186:189], v[16:19]
	v_mfma_f32_16x16x32_bf16 v[12:15], v[162:165], v[198:201], v[12:15]
	v_mfma_f32_16x16x32_bf16 v[8:11], v[170:173], v[198:201], v[8:11]
	v_mfma_f32_16x16x32_bf16 v[4:7], v[162:165], v[206:209], v[4:7]
	v_mfma_f32_16x16x32_bf16 v[0:3], v[170:173], v[206:209], v[0:3]
	v_mfma_f32_16x16x32_bf16 v[28:31], v[166:169], v[182:185], v[28:31]
	v_mfma_f32_16x16x32_bf16 v[24:27], v[174:177], v[182:185], v[24:27]
	v_mfma_f32_16x16x32_bf16 v[20:23], v[166:169], v[194:197], v[20:23]
	v_mfma_f32_16x16x32_bf16 v[16:19], v[174:177], v[194:197], v[16:19]
	v_mfma_f32_16x16x32_bf16 v[12:15], v[166:169], v[202:205], v[12:15]
	v_mfma_f32_16x16x32_bf16 v[8:11], v[174:177], v[202:205], v[8:11]
	v_mfma_f32_16x16x32_bf16 v[4:7], v[166:169], v[210:213], v[4:7]
	v_mfma_f32_16x16x32_bf16 v[0:3], v[174:177], v[210:213], v[0:3]
	s_add_u32 s23, s23, 0x100
	s_addc_u32 s87, s87, 0
	s_cmp_ge_i32 s88, s19
	s_mov_b64 s[34:35], s[36:37]
	s_mov_b32 s64, s88
	s_setprio 0
	s_barrier
	s_cbranch_scc0 .LBB0_905
	s_and_b64 vcc, exec, s[48:49]
	s_cbranch_vccz .LBB0_911

; #define PG8_STAGE(bufoff, gbase, voff) do { _Pragma("unroll") for (int _i = 0; _i < 2; ++_i) \
;         __builtin_amdgcn_global_load_lds((const unsigned*)((const char*)(gbase) + (voff)[_i]), (LAS unsigned*)(lds + (bufoff) + ldsw + _i * 8192), 16, 0, 0); } while (0)
; #define PG8_LDA(dst, b, h) do { _Pragma("unroll") for (int m = 0; m < 4; ++m) _Pragma("unroll") for (int k = 0; k < 2; ++k) dst[m][k] = *(const LAS bf16x8*)(lds + PG8_SA(b, h) + aoff + m * 2048 + k * 1024); } while (0)
; #define PG8_LDB(dst, b, h) do { _Pragma("unroll") for (int n = 0; n < 2; ++n) _Pragma("unroll") for (int k = 0; k < 2; ++k) dst[n][k] = *(const LAS bf16x8*)(lds + PG8_SB(b, h) + boff + n * 2048 + k * 1024); } while (0)
; #define PG8_MMA(ai, bj, At, Bt) do { __builtin_amdgcn_s_setprio(1); _Pragma("unroll") for (int m = 0; m < 4; ++m) _Pragma("unroll") for (int n = 0; n < 2; ++n) _Pragma("unroll") for (int k = 0; k < 2; ++k) \
;         acc[ai][bj][m][n] = __builtin_amdgcn_mfma_f32_16x16x32_bf16(Bt[n][k], At[m][k], acc[ai][bj][m][n], 0, 0, 0); __builtin_amdgcn_s_setprio(0); } while (0)
; #define PG8_WAIT_V(n) asm volatile("s_waitcnt vmcnt(" #n ")" ::: "memory")
; #define PG8_WAIT_L(n) asm volatile("s_waitcnt lgkmcnt(" #n ")" ::: "memory")
; #define PG8_BAR __builtin_amdgcn_s_barrier()
; #define PG8_SCHED __builtin_amdgcn_sched_barrier(0)
; template <class Epi, class Sched>
; __device__ __forceinline__ void gemm_phase(LAS unsigned char* lds, const Gemm g, const Sched& S, const Epi& E, float* part, int wave) {
;     ...
;         for (int t = 0; t < nt; t += 2) {
;             const bool last = (t == nt - 2);
;             const char* a1 = cA + (size_t)(t + 1) * kstep;
;             const char* a2 = last ? nA : cA + (size_t)(t + 2) * kstep; const char* b2 = last ? nB : cB + (size_t)(t + 2) * kstep;
;             const char* a3 = a2 + kstep; const char* b3 = b2 + kstep;
;             PG8_LDB(B0, 0, 0); PG8_LDB(B1, 0, 1); PG8_SCHED; PG8_LDA(At, 0, 0); PG8_STAGE(PG8_SA(1, 1), a1 + hstep, voffA);
;             PG8_WAIT_V(8); PG8_WAIT_L(0); PG8_BAR; PG8_MMA(0, 0, At, B0); PG8_MMA(0, 1, At, B1); PG8_BAR; PG8_SCHED;
;             PG8_LDA(At, 0, 1); PG8_STAGE(PG8_SB(0, 0), b2, voffB); PG8_STAGE(PG8_SB(0, 1), b2 + hstep, voffB); PG8_STAGE(PG8_SA(0, 0), a2, voffA);
;             PG8_WAIT_V(8); PG8_WAIT_L(0); PG8_BAR; PG8_MMA(1, 0, At, B0); PG8_MMA(1, 1, At, B1); PG8_BAR; PG8_SCHED;
.LBB0_1106:
	ds_read_b128 v[144:147], v151
	ds_read_b128 v[154:157], v151 offset:1024
	ds_read_b128 v[158:161], v151 offset:2048
	ds_read_b128 v[162:165], v151 offset:3072
	ds_read_b128 v[166:169], v152
	ds_read_b128 v[170:173], v152 offset:1024
	ds_read_b128 v[174:177], v152 offset:2048
	ds_read_b128 v[178:181], v152 offset:3072
	s_add_i32 s89, s64, 2
	s_add_u32 s65, s36, 0xfff00080
	s_addc_u32 s66, s37, -1
	s_cmp_eq_u32 s23, s64
	s_cselect_b32 s64, s28, s25
	s_cselect_b32 s67, s27, s66
	s_cselect_b32 s66, s26, s65
	s_cselect_b32 s65, s29, s88
	v_lshl_add_u64 v[190:191], s[36:37], 0, v[140:141]
	s_add_i32 m0, s31, 0xc000
	ds_read_b128 v[182:185], v153
	ds_read_b128 v[186:189], v153 offset:1024
	ds_read_b128 v[194:197], v153 offset:2048
	ds_read_b128 v[198:201], v153 offset:3072
	ds_read_b128 v[202:205], v153 offset:4096
	ds_read_b128 v[206:209], v153 offset:5120
	ds_read_b128 v[210:213], v153 offset:6144
	ds_read_b128 v[214:217], v153 offset:7168
	global_load_lds_dwordx4 v[190:191], off
	v_lshl_add_u64 v[190:191], s[36:37], 0, v[138:139]
	s_add_i32 m0, s31, 0xe000
	s_nop 0
	global_load_lds_dwordx4 v[190:191], off
	s_waitcnt vmcnt(8)
	s_waitcnt lgkmcnt(0)
	s_barrier
	s_setprio 1
	s_waitcnt lgkmcnt(0)
	v_mfma_f32_16x16x32_bf16 v[124:127], v[144:147], v[182:185], v[124:127]
	v_mfma_f32_16x16x32_bf16 v[120:123], v[158:161], v[182:185], v[120:123]
	v_mfma_f32_16x16x32_bf16 v[116:119], v[144:147], v[194:197], v[116:119]
	v_mfma_f32_16x16x32_bf16 v[112:115], v[158:161], v[194:197], v[112:115]
	v_mfma_f32_16x16x32_bf16 v[108:111], v[144:147], v[202:205], v[108:111]
	v_mfma_f32_16x16x32_bf16 v[104:107], v[158:161], v[202:205], v[104:107]
	v_mfma_f32_16x16x32_bf16 v[100:103], v[144:147], v[210:213], v[100:103]
	v_mfma_f32_16x16x32_bf16 v[96:99], v[158:161], v[210:213], v[96:99]
	v_mfma_f32_16x16x32_bf16 v[124:127], v[154:157], v[186:189], v[124:127]
	v_mfma_f32_16x16x32_bf16 v[120:123], v[162:165], v[186:189], v[120:123]
	v_mfma_f32_16x16x32_bf16 v[116:119], v[154:157], v[198:201], v[116:119]
	v_mfma_f32_16x16x32_bf16 v[112:115], v[162:165], v[198:201], v[112:115]
	v_mfma_f32_16x16x32_bf16 v[108:111], v[154:157], v[206:209], v[108:111]
	v_mfma_f32_16x16x32_bf16 v[104:107], v[162:165], v[206:209], v[104:107]
	v_mfma_f32_16x16x32_bf16 v[100:103], v[154:157], v[214:217], v[100:103]
	v_mfma_f32_16x16x32_bf16 v[96:99], v[162:165], v[214:217], v[96:99]
	s_setprio 0
	s_setprio 1
	v_mfma_f32_16x16x32_bf16 v[92:95], v[166:169], v[182:185], v[92:95]
	v_mfma_f32_16x16x32_bf16 v[88:91], v[174:177], v[182:185], v[88:91]
	v_mfma_f32_16x16x32_bf16 v[84:87], v[166:169], v[194:197], v[84:87]
	v_mfma_f32_16x16x32_bf16 v[80:83], v[174:177], v[194:197], v[80:83]
	v_mfma_f32_16x16x32_bf16 v[76:79], v[166:169], v[202:205], v[76:79]
	v_mfma_f32_16x16x32_bf16 v[72:75], v[174:177], v[202:205], v[72:75]
	v_mfma_f32_16x16x32_bf16 v[68:71], v[166:169], v[210:213], v[68:71]
	v_mfma_f32_16x16x32_bf16 v[64:67], v[174:177], v[210:213], v[64:67]
	v_mfma_f32_16x16x32_bf16 v[92:95], v[170:173], v[186:189], v[92:95]
	v_mfma_f32_16x16x32_bf16 v[88:91], v[178:181], v[186:189], v[88:91]
	v_mfma_f32_16x16x32_bf16 v[84:87], v[170:173], v[198:201], v[84:87]
	v_mfma_f32_16x16x32_bf16 v[80:83], v[178:181], v[198:201], v[80:83]
	v_mfma_f32_16x16x32_bf16 v[76:79], v[170:173], v[206:209], v[76:79]
	v_mfma_f32_16x16x32_bf16 v[72:75], v[178:181], v[206:209], v[72:75]
	v_mfma_f32_16x16x32_bf16 v[68:71], v[170:173], v[214:217], v[68:71]
	v_mfma_f32_16x16x32_bf16 v[64:67], v[178:181], v[214:217], v[64:67]
	s_setprio 0
	s_barrier
	s_add_i32 s90, s78, s91
	v_lshl_add_u64 v[190:191], s[64:65], 0, v[130:131]
	s_mov_b32 m0, s90
	ds_read_b128 v[182:185], v153 offset:16384
	ds_read_b128 v[186:189], v153 offset:17408
	ds_read_b128 v[194:197], v153 offset:18432
	ds_read_b128 v[198:201], v153 offset:19456
	ds_read_b128 v[202:205], v153 offset:20480
	ds_read_b128 v[206:209], v153 offset:21504
	ds_read_b128 v[210:213], v153 offset:22528
	ds_read_b128 v[214:217], v153 offset:23552
	global_load_lds_dwordx4 v[190:191], off
	s_add_i32 m0, s90, 0x2000
	s_add_u32 s92, s64, 0x100000
	v_lshl_add_u64 v[218:219], s[64:65], 0, v[134:135]
	s_addc_u32 s93, s65, 0
	s_add_i32 s90, s79, s91
	global_load_lds_dwordx4 v[218:219], off
	v_lshl_add_u64 v[220:221], s[92:93], 0, v[130:131]
	s_mov_b32 m0, s90
	v_lshl_add_u64 v[222:223], s[66:67], 0, v[132:133]
	global_load_lds_dwordx4 v[220:221], off
	v_lshl_add_u64 v[220:221], s[92:93], 0, v[134:135]
	s_add_i32 m0, s90, 0x2000
	s_nop 0
	global_load_lds_dwordx4 v[220:221], off
	v_lshl_add_u64 v[220:221], s[66:67], 0, v[128:129]
	s_mov_b32 m0, s31
	s_nop 0
	global_load_lds_dwordx4 v[220:221], off
	s_mov_b32 m0, s33
	s_nop 0
	global_load_lds_dwordx4 v[222:223], off
	s_waitcnt vmcnt(8)
	s_waitcnt lgkmcnt(0)
	s_barrier
; #define PG8_STAGE(bufoff, gbase, voff) do { _Pragma("unroll") for (int _i = 0; _i < 2; ++_i) \
;         __builtin_amdgcn_global_load_lds((const unsigned*)((const char*)(gbase) + (voff)[_i]), (LAS unsigned*)(lds + (bufoff) + ldsw + _i * 8192), 16, 0, 0); } while (0)
; #define PG8_LDA(dst, b, h) do { _Pragma("unroll") for (int m = 0; m < 4; ++m) _Pragma("unroll") for (int k = 0; k < 2; ++k) dst[m][k] = *(const LAS bf16x8*)(lds + PG8_SA(b, h) + aoff + m * 2048 + k * 1024); } while (0)
; #define PG8_LDB(dst, b, h) do { _Pragma("unroll") for (int n = 0; n < 2; ++n) _Pragma("unroll") for (int k = 0; k < 2; ++k) dst[n][k] = *(const LAS bf16x8*)(lds + PG8_SB(b, h) + boff + n * 2048 + k * 1024); } while (0)
; #define PG8_MMA(ai, bj, At, Bt) do { __builtin_amdgcn_s_setprio(1); _Pragma("unroll") for (int m = 0; m < 4; ++m) _Pragma("unroll") for (int n = 0; n < 2; ++n) _Pragma("unroll") for (int k = 0; k < 2; ++k) \
;         acc[ai][bj][m][n] = __builtin_amdgcn_mfma_f32_16x16x32_bf16(Bt[n][k], At[m][k], acc[ai][bj][m][n], 0, 0, 0); __builtin_amdgcn_s_setprio(0); } while (0)
; #define PG8_WAIT_V(n) asm volatile("s_waitcnt vmcnt(" #n ")" ::: "memory")
; #define PG8_WAIT_L(n) asm volatile("s_waitcnt lgkmcnt(" #n ")" ::: "memory")
; #define PG8_BAR __builtin_amdgcn_s_barrier()
; #define PG8_SCHED __builtin_amdgcn_sched_barrier(0)
; template <class Epi, class Sched>
; __device__ __forceinline__ void gemm_phase(LAS unsigned char* lds, const Gemm g, const Sched& S, const Epi& E, float* part, int wave) {
;     ...
;             PG8_WAIT_V(8); PG8_WAIT_L(0); PG8_BAR; PG8_MMA(1, 0, At, B0); PG8_MMA(1, 1, At, B1); PG8_BAR; PG8_SCHED;
;             PG8_LDB(B0, 1, 0); PG8_LDB(B1, 1, 1); PG8_SCHED; PG8_LDA(At, 1, 0); PG8_STAGE(PG8_SA(0, 1), a2 + hstep, voffA);
;             PG8_WAIT_V(8); PG8_WAIT_L(0); PG8_BAR; PG8_MMA(0, 0, At, B0); PG8_MMA(0, 1, At, B1); PG8_BAR; PG8_SCHED;
	s_setprio 1
	s_waitcnt lgkmcnt(0)
	v_mfma_f32_16x16x32_bf16 v[60:63], v[144:147], v[182:185], v[60:63]
	v_mfma_f32_16x16x32_bf16 v[56:59], v[158:161], v[182:185], v[56:59]
	v_mfma_f32_16x16x32_bf16 v[52:55], v[144:147], v[194:197], v[52:55]
	v_mfma_f32_16x16x32_bf16 v[48:51], v[158:161], v[194:197], v[48:51]
	v_mfma_f32_16x16x32_bf16 v[44:47], v[144:147], v[202:205], v[44:47]
	v_mfma_f32_16x16x32_bf16 v[40:43], v[158:161], v[202:205], v[40:43]
	v_mfma_f32_16x16x32_bf16 v[36:39], v[144:147], v[210:213], v[36:39]
	v_mfma_f32_16x16x32_bf16 v[32:35], v[158:161], v[210:213], v[32:35]
	v_mfma_f32_16x16x32_bf16 v[60:63], v[154:157], v[186:189], v[60:63]
	v_mfma_f32_16x16x32_bf16 v[56:59], v[162:165], v[186:189], v[56:59]
	v_mfma_f32_16x16x32_bf16 v[52:55], v[154:157], v[198:201], v[52:55]
	v_mfma_f32_16x16x32_bf16 v[48:51], v[162:165], v[198:201], v[48:51]
	v_mfma_f32_16x16x32_bf16 v[44:47], v[154:157], v[206:209], v[44:47]
	v_mfma_f32_16x16x32_bf16 v[40:43], v[162:165], v[206:209], v[40:43]
	v_mfma_f32_16x16x32_bf16 v[36:39], v[154:157], v[214:217], v[36:39]
	v_mfma_f32_16x16x32_bf16 v[32:35], v[162:165], v[214:217], v[32:35]
	s_setprio 0
	s_setprio 1
	v_mfma_f32_16x16x32_bf16 v[28:31], v[166:169], v[182:185], v[28:31]
	v_mfma_f32_16x16x32_bf16 v[24:27], v[174:177], v[182:185], v[24:27]
	v_mfma_f32_16x16x32_bf16 v[20:23], v[166:169], v[194:197], v[20:23]
	v_mfma_f32_16x16x32_bf16 v[16:19], v[174:177], v[194:197], v[16:19]
	v_mfma_f32_16x16x32_bf16 v[12:15], v[166:169], v[202:205], v[12:15]
	v_mfma_f32_16x16x32_bf16 v[8:11], v[174:177], v[202:205], v[8:11]
	v_mfma_f32_16x16x32_bf16 v[4:7], v[166:169], v[210:213], v[4:7]
	v_mfma_f32_16x16x32_bf16 v[0:3], v[174:177], v[210:213], v[0:3]
	v_mfma_f32_16x16x32_bf16 v[28:31], v[170:173], v[186:189], v[28:31]
	v_mfma_f32_16x16x32_bf16 v[24:27], v[178:181], v[186:189], v[24:27]
	v_mfma_f32_16x16x32_bf16 v[20:23], v[170:173], v[198:201], v[20:23]
	v_mfma_f32_16x16x32_bf16 v[16:19], v[178:181], v[198:201], v[16:19]
	v_mfma_f32_16x16x32_bf16 v[12:15], v[170:173], v[206:209], v[12:15]
	v_mfma_f32_16x16x32_bf16 v[8:11], v[178:181], v[206:209], v[8:11]
	v_mfma_f32_16x16x32_bf16 v[4:7], v[170:173], v[214:217], v[4:7]
	v_mfma_f32_16x16x32_bf16 v[0:3], v[178:181], v[214:217], v[0:3]
	s_setprio 0
	s_barrier
	s_add_i32 s90, 0, 0x18000
	s_add_i32 s92, 0, 0x1c000
	v_add_u32_e32 v162, s90, v149
	v_add_u32_e32 v178, s92, v149
	ds_read_b128 v[144:147], v162
	ds_read_b128 v[154:157], v162 offset:1024
	ds_read_b128 v[158:161], v162 offset:2048
	ds_read_b128 v[162:165], v162 offset:3072
	ds_read_b128 v[166:169], v178
	ds_read_b128 v[170:173], v178 offset:1024
	ds_read_b128 v[174:177], v178 offset:2048
	ds_read_b128 v[178:181], v178 offset:3072
	s_add_u32 s66, s66, 0x100000
	s_addc_u32 s67, s67, 0
	s_mov_b32 m0, s35
	v_lshl_add_u64 v[224:225], s[66:67], 0, v[128:129]
	ds_read_b128 v[182:185], v153 offset:32768
	ds_read_b128 v[186:189], v153 offset:33792
	ds_read_b128 v[194:197], v153 offset:34816
	ds_read_b128 v[198:201], v153 offset:35840
	ds_read_b128 v[202:205], v153 offset:36864
	ds_read_b128 v[206:209], v153 offset:37888
	ds_read_b128 v[210:213], v153 offset:38912
	ds_read_b128 v[214:217], v153 offset:39936
	global_load_lds_dwordx4 v[224:225], off
	v_lshl_add_u64 v[224:225], s[66:67], 0, v[132:133]
	s_mov_b32 m0, s39
	s_nop 0
	global_load_lds_dwordx4 v[224:225], off
	s_waitcnt vmcnt(8)
	s_waitcnt lgkmcnt(0)
	s_barrier
	s_setprio 1
	s_waitcnt lgkmcnt(0)
	v_mfma_f32_16x16x32_bf16 v[124:127], v[144:147], v[182:185], v[124:127]
	v_mfma_f32_16x16x32_bf16 v[120:123], v[158:161], v[182:185], v[120:123]
	v_mfma_f32_16x16x32_bf16 v[116:119], v[144:147], v[194:197], v[116:119]
	v_mfma_f32_16x16x32_bf16 v[112:115], v[158:161], v[194:197], v[112:115]
	v_mfma_f32_16x16x32_bf16 v[108:111], v[144:147], v[202:205], v[108:111]
	v_mfma_f32_16x16x32_bf16 v[104:107], v[158:161], v[202:205], v[104:107]
	v_mfma_f32_16x16x32_bf16 v[100:103], v[144:147], v[210:213], v[100:103]
	v_mfma_f32_16x16x32_bf16 v[96:99], v[158:161], v[210:213], v[96:99]
	v_mfma_f32_16x16x32_bf16 v[124:127], v[154:157], v[186:189], v[124:127]
	v_mfma_f32_16x16x32_bf16 v[120:123], v[162:165], v[186:189], v[120:123]
	v_mfma_f32_16x16x32_bf16 v[116:119], v[154:157], v[198:201], v[116:119]
	v_mfma_f32_16x16x32_bf16 v[112:115], v[162:165], v[198:201], v[112:115]
	v_mfma_f32_16x16x32_bf16 v[108:111], v[154:157], v[206:209], v[108:111]
	v_mfma_f32_16x16x32_bf16 v[104:107], v[162:165], v[206:209], v[104:107]
	v_mfma_f32_16x16x32_bf16 v[100:103], v[154:157], v[214:217], v[100:103]
	v_mfma_f32_16x16x32_bf16 v[96:99], v[162:165], v[214:217], v[96:99]
	s_setprio 0
	s_setprio 1
	v_mfma_f32_16x16x32_bf16 v[92:95], v[166:169], v[182:185], v[92:95]
	v_mfma_f32_16x16x32_bf16 v[88:91], v[174:177], v[182:185], v[88:91]
	v_mfma_f32_16x16x32_bf16 v[84:87], v[166:169], v[194:197], v[84:87]
	v_mfma_f32_16x16x32_bf16 v[80:83], v[174:177], v[194:197], v[80:83]
	v_mfma_f32_16x16x32_bf16 v[76:79], v[166:169], v[202:205], v[76:79]
	v_mfma_f32_16x16x32_bf16 v[72:75], v[174:177], v[202:205], v[72:75]
	v_mfma_f32_16x16x32_bf16 v[68:71], v[166:169], v[210:213], v[68:71]
	v_mfma_f32_16x16x32_bf16 v[64:67], v[174:177], v[210:213], v[64:67]
	v_mfma_f32_16x16x32_bf16 v[92:95], v[170:173], v[186:189], v[92:95]
	v_mfma_f32_16x16x32_bf16 v[88:91], v[178:181], v[186:189], v[88:91]
	v_mfma_f32_16x16x32_bf16 v[84:87], v[170:173], v[198:201], v[84:87]
	v_mfma_f32_16x16x32_bf16 v[80:83], v[178:181], v[198:201], v[80:83]
	v_mfma_f32_16x16x32_bf16 v[76:79], v[170:173], v[206:209], v[76:79]
	v_mfma_f32_16x16x32_bf16 v[72:75], v[178:181], v[206:209], v[72:75]
	v_mfma_f32_16x16x32_bf16 v[68:71], v[170:173], v[214:217], v[68:71]
	v_mfma_f32_16x16x32_bf16 v[64:67], v[178:181], v[214:217], v[64:67]
	s_setprio 0
	s_barrier
; #define PG8_STAGE(bufoff, gbase, voff) do { _Pragma("unroll") for (int _i = 0; _i < 2; ++_i) \
;         __builtin_amdgcn_global_load_lds((const unsigned*)((const char*)(gbase) + (voff)[_i]), (LAS unsigned*)(lds + (bufoff) + ldsw + _i * 8192), 16, 0, 0); } while (0)
; #define PG8_LDA(dst, b, h) do { _Pragma("unroll") for (int m = 0; m < 4; ++m) _Pragma("unroll") for (int k = 0; k < 2; ++k) dst[m][k] = *(const LAS bf16x8*)(lds + PG8_SA(b, h) + aoff + m * 2048 + k * 1024); } while (0)
; #define PG8_MMA(ai, bj, At, Bt) do { __builtin_amdgcn_s_setprio(1); _Pragma("unroll") for (int m = 0; m < 4; ++m) _Pragma("unroll") for (int n = 0; n < 2; ++n) _Pragma("unroll") for (int k = 0; k < 2; ++k) \
;         acc[ai][bj][m][n] = __builtin_amdgcn_mfma_f32_16x16x32_bf16(Bt[n][k], At[m][k], acc[ai][bj][m][n], 0, 0, 0); __builtin_amdgcn_s_setprio(0); } while (0)
; #define PG8_WAIT_V(n) asm volatile("s_waitcnt vmcnt(" #n ")" ::: "memory")
; #define PG8_WAIT_L(n) asm volatile("s_waitcnt lgkmcnt(" #n ")" ::: "memory")
; #define PG8_BAR __builtin_amdgcn_s_barrier()
; #define PG8_SCHED __builtin_amdgcn_sched_barrier(0)
; template <class Epi, class Sched>
; __device__ __forceinline__ void gemm_phase(LAS unsigned char* lds, const Gemm g, const Sched& S, const Epi& E, float* part, int wave) {
;     ...
;             PG8_LDA(At, 1, 1); PG8_STAGE(PG8_SB(1, 0), b3, voffB); PG8_STAGE(PG8_SB(1, 1), b3 + hstep, voffB); PG8_STAGE(PG8_SA(1, 0), a3, voffA);
;             PG8_WAIT_V(8); PG8_WAIT_L(0); PG8_BAR; PG8_MMA(1, 0, At, B0); PG8_MMA(1, 1, At, B1); PG8_BAR; PG8_SCHED;
;         }
	s_add_i32 s66, s90, s91
	v_lshl_add_u64 v[190:191], v[190:191], 0, s[14:15]
	s_mov_b32 m0, s66
	ds_read_b128 v[182:185], v153 offset:49152
	ds_read_b128 v[186:189], v153 offset:50176
	ds_read_b128 v[194:197], v153 offset:51200
	ds_read_b128 v[198:201], v153 offset:52224
	ds_read_b128 v[202:205], v153 offset:53248
	ds_read_b128 v[206:209], v153 offset:54272
	ds_read_b128 v[210:213], v153 offset:55296
	ds_read_b128 v[214:217], v153 offset:56320
	global_load_lds_dwordx4 v[190:191], off
	s_add_i32 m0, s66, 0x2000
	s_add_u32 s64, s64, 0x100080
	v_lshl_add_u64 v[190:191], v[218:219], 0, s[14:15]
	s_addc_u32 s65, s65, 0
	s_add_i32 s66, s92, s91
	global_load_lds_dwordx4 v[190:191], off
	v_lshl_add_u64 v[190:191], s[64:65], 0, v[130:131]
	s_mov_b32 m0, s66
	s_nop 0
	global_load_lds_dwordx4 v[190:191], off
	v_lshl_add_u64 v[190:191], s[64:65], 0, v[134:135]
	s_add_i32 m0, s66, 0x2000
	s_nop 0
	global_load_lds_dwordx4 v[190:191], off
	v_lshl_add_u64 v[190:191], v[220:221], 0, s[14:15]
	s_mov_b32 m0, s41
	s_nop 0
	global_load_lds_dwordx4 v[190:191], off
	v_lshl_add_u64 v[190:191], v[222:223], 0, s[14:15]
	s_mov_b32 m0, s63
	s_nop 0
	global_load_lds_dwordx4 v[190:191], off
	s_waitcnt vmcnt(8)
	s_waitcnt lgkmcnt(0)
	s_barrier
	s_setprio 1
	s_waitcnt lgkmcnt(0)
	v_mfma_f32_16x16x32_bf16 v[60:63], v[144:147], v[182:185], v[60:63]
	v_mfma_f32_16x16x32_bf16 v[56:59], v[158:161], v[182:185], v[56:59]
	v_mfma_f32_16x16x32_bf16 v[52:55], v[144:147], v[194:197], v[52:55]
	v_mfma_f32_16x16x32_bf16 v[48:51], v[158:161], v[194:197], v[48:51]
	v_mfma_f32_16x16x32_bf16 v[44:47], v[144:147], v[202:205], v[44:47]
	v_mfma_f32_16x16x32_bf16 v[40:43], v[158:161], v[202:205], v[40:43]
	v_mfma_f32_16x16x32_bf16 v[36:39], v[144:147], v[210:213], v[36:39]
	v_mfma_f32_16x16x32_bf16 v[32:35], v[158:161], v[210:213], v[32:35]
	v_mfma_f32_16x16x32_bf16 v[60:63], v[154:157], v[186:189], v[60:63]
	v_mfma_f32_16x16x32_bf16 v[56:59], v[162:165], v[186:189], v[56:59]
	v_mfma_f32_16x16x32_bf16 v[52:55], v[154:157], v[198:201], v[52:55]
	v_mfma_f32_16x16x32_bf16 v[48:51], v[162:165], v[198:201], v[48:51]
	v_mfma_f32_16x16x32_bf16 v[44:47], v[154:157], v[206:209], v[44:47]
	v_mfma_f32_16x16x32_bf16 v[40:43], v[162:165], v[206:209], v[40:43]
	v_mfma_f32_16x16x32_bf16 v[36:39], v[154:157], v[214:217], v[36:39]
	v_mfma_f32_16x16x32_bf16 v[32:35], v[162:165], v[214:217], v[32:35]
	s_setprio 0
	s_setprio 1
	v_mfma_f32_16x16x32_bf16 v[28:31], v[166:169], v[182:185], v[28:31]
	v_mfma_f32_16x16x32_bf16 v[24:27], v[174:177], v[182:185], v[24:27]
	v_mfma_f32_16x16x32_bf16 v[20:23], v[166:169], v[194:197], v[20:23]
	v_mfma_f32_16x16x32_bf16 v[16:19], v[174:177], v[194:197], v[16:19]
	v_mfma_f32_16x16x32_bf16 v[12:15], v[166:169], v[202:205], v[12:15]
	v_mfma_f32_16x16x32_bf16 v[8:11], v[174:177], v[202:205], v[8:11]
	v_mfma_f32_16x16x32_bf16 v[4:7], v[166:169], v[210:213], v[4:7]
	v_mfma_f32_16x16x32_bf16 v[0:3], v[174:177], v[210:213], v[0:3]
	v_mfma_f32_16x16x32_bf16 v[28:31], v[170:173], v[186:189], v[28:31]
	v_mfma_f32_16x16x32_bf16 v[24:27], v[178:181], v[186:189], v[24:27]
	v_mfma_f32_16x16x32_bf16 v[20:23], v[170:173], v[198:201], v[20:23]
	v_mfma_f32_16x16x32_bf16 v[16:19], v[178:181], v[198:201], v[16:19]
	v_mfma_f32_16x16x32_bf16 v[12:15], v[170:173], v[206:209], v[12:15]
	v_mfma_f32_16x16x32_bf16 v[8:11], v[178:181], v[206:209], v[8:11]
	v_mfma_f32_16x16x32_bf16 v[4:7], v[170:173], v[214:217], v[4:7]
	v_mfma_f32_16x16x32_bf16 v[0:3], v[178:181], v[214:217], v[0:3]
	s_add_u32 s25, s25, 0x100
	s_addc_u32 s88, s88, 0
	s_add_u32 s36, s36, 0x100
	s_addc_u32 s37, s37, 0
	s_cmp_ge_i32 s89, s21
	s_mov_b32 s64, s89
	s_setprio 0
	s_barrier
	s_cbranch_scc0 .LBB0_1106
	s_and_b64 vcc, exec, s[48:49]
	s_cbranch_vccz .LBB0_1112

; #define PG8_STAGE(bufoff, gbase, voff) do { _Pragma("unroll") for (int _i = 0; _i < 2; ++_i) \
;         __builtin_amdgcn_global_load_lds((const unsigned*)((const char*)(gbase) + (voff)[_i]), (LAS unsigned*)(lds + (bufoff) + ldsw + _i * 8192), 16, 0, 0); } while (0)
; #define PG8_LDA(dst, b, h) do { _Pragma("unroll") for (int m = 0; m < 4; ++m) _Pragma("unroll") for (int k = 0; k < 2; ++k) dst[m][k] = *(const LAS bf16x8*)(lds + PG8_SA(b, h) + aoff + m * 2048 + k * 1024); } while (0)
; #define PG8_LDB(dst, b, h) do { _Pragma("unroll") for (int n = 0; n < 2; ++n) _Pragma("unroll") for (int k = 0; k < 2; ++k) dst[n][k] = *(const LAS bf16x8*)(lds + PG8_SB(b, h) + boff + n * 2048 + k * 1024); } while (0)
; #define PG8_MMA(ai, bj, At, Bt) do { __builtin_amdgcn_s_setprio(1); _Pragma("unroll") for (int m = 0; m < 4; ++m) _Pragma("unroll") for (int n = 0; n < 2; ++n) _Pragma("unroll") for (int k = 0; k < 2; ++k) \
;         acc[ai][bj][m][n] = __builtin_amdgcn_mfma_f32_16x16x32_bf16(Bt[n][k], At[m][k], acc[ai][bj][m][n], 0, 0, 0); __builtin_amdgcn_s_setprio(0); } while (0)
; #define PG8_WAIT_V(n) asm volatile("s_waitcnt vmcnt(" #n ")" ::: "memory")
; #define PG8_WAIT_L(n) asm volatile("s_waitcnt lgkmcnt(" #n ")" ::: "memory")
; #define PG8_BAR __builtin_amdgcn_s_barrier()
; #define PG8_SCHED __builtin_amdgcn_sched_barrier(0)
; template <class Epi, class Sched>
; __device__ __forceinline__ void gemm_phase(LAS unsigned char* lds, const Gemm g, const Sched& S, const Epi& E, float* part, int wave) {
;     ...
;         for (int t = 0; t < nt; t += 2) {
;             const bool last = (t == nt - 2);
;             const char* a1 = cA + (size_t)(t + 1) * kstep;
;             const char* a2 = last ? nA : cA + (size_t)(t + 2) * kstep; const char* b2 = last ? nB : cB + (size_t)(t + 2) * kstep;
;             const char* a3 = a2 + kstep; const char* b3 = b2 + kstep;
;             PG8_LDB(B0, 0, 0); PG8_LDB(B1, 0, 1); PG8_SCHED; PG8_LDA(At, 0, 0); PG8_STAGE(PG8_SA(1, 1), a1 + hstep, voffA);
;             PG8_WAIT_V(8); PG8_WAIT_L(0); PG8_BAR; PG8_MMA(0, 0, At, B0); PG8_MMA(0, 1, At, B1); PG8_BAR; PG8_SCHED;
;             PG8_LDA(At, 0, 1); PG8_STAGE(PG8_SB(0, 0), b2, voffB); PG8_STAGE(PG8_SB(0, 1), b2 + hstep, voffB); PG8_STAGE(PG8_SA(0, 0), a2, voffA);
;             PG8_WAIT_V(8); PG8_WAIT_L(0); PG8_BAR; PG8_MMA(1, 0, At, B0); PG8_MMA(1, 1, At, B1); PG8_BAR; PG8_SCHED;
.LBB0_1249:
	ds_read_b128 v[140:143], v147
	ds_read_b128 v[150:153], v147 offset:1024
	ds_read_b128 v[154:157], v147 offset:2048
	ds_read_b128 v[158:161], v147 offset:3072
	ds_read_b128 v[162:165], v148
	ds_read_b128 v[166:169], v148 offset:1024
	ds_read_b128 v[170:173], v148 offset:2048
	ds_read_b128 v[174:177], v148 offset:3072
	s_add_i32 s96, s30, 2
	s_add_u32 s28, s26, 0x100
	s_addc_u32 s29, s27, 0
	s_cmp_eq_u32 s93, s30
	s_cselect_b32 s30, s24, s94
	s_cselect_b32 s35, s23, s29
	s_cselect_b32 s34, s22, s28
	s_cselect_b32 s31, s25, s95
	v_lshl_add_u64 v[190:191], s[26:27], 0, v[136:137]
	s_add_i32 m0, s5, 0xc000
	ds_read_b128 v[178:181], v149
	ds_read_b128 v[182:185], v149 offset:1024
	ds_read_b128 v[186:189], v149 offset:2048
	ds_read_b128 v[194:197], v149 offset:3072
	ds_read_b128 v[198:201], v149 offset:4096
	ds_read_b128 v[202:205], v149 offset:5120
	ds_read_b128 v[206:209], v149 offset:6144
	ds_read_b128 v[210:213], v149 offset:7168
	global_load_lds_dwordx4 v[190:191], off
	v_lshl_add_u64 v[190:191], s[26:27], 0, v[134:135]
	s_add_i32 m0, s5, 0xe000
	s_nop 0
	global_load_lds_dwordx4 v[190:191], off
	s_waitcnt vmcnt(8)
	s_waitcnt lgkmcnt(0)
	s_barrier
	s_setprio 1
	s_waitcnt lgkmcnt(0)
	v_mfma_f32_16x16x32_bf16 v[124:127], v[140:143], v[178:181], v[124:127]
	v_mfma_f32_16x16x32_bf16 v[120:123], v[154:157], v[178:181], v[120:123]
	v_mfma_f32_16x16x32_bf16 v[116:119], v[140:143], v[186:189], v[116:119]
	v_mfma_f32_16x16x32_bf16 v[112:115], v[154:157], v[186:189], v[112:115]
	v_mfma_f32_16x16x32_bf16 v[108:111], v[140:143], v[198:201], v[108:111]
	v_mfma_f32_16x16x32_bf16 v[104:107], v[154:157], v[198:201], v[104:107]
	v_mfma_f32_16x16x32_bf16 v[100:103], v[140:143], v[206:209], v[100:103]
	v_mfma_f32_16x16x32_bf16 v[96:99], v[154:157], v[206:209], v[96:99]
	v_mfma_f32_16x16x32_bf16 v[124:127], v[150:153], v[182:185], v[124:127]
	v_mfma_f32_16x16x32_bf16 v[120:123], v[158:161], v[182:185], v[120:123]
	v_mfma_f32_16x16x32_bf16 v[116:119], v[150:153], v[194:197], v[116:119]
	v_mfma_f32_16x16x32_bf16 v[112:115], v[158:161], v[194:197], v[112:115]
	v_mfma_f32_16x16x32_bf16 v[108:111], v[150:153], v[202:205], v[108:111]
	v_mfma_f32_16x16x32_bf16 v[104:107], v[158:161], v[202:205], v[104:107]
	v_mfma_f32_16x16x32_bf16 v[100:103], v[150:153], v[210:213], v[100:103]
	v_mfma_f32_16x16x32_bf16 v[96:99], v[158:161], v[210:213], v[96:99]
	s_setprio 0
	s_setprio 1
	v_mfma_f32_16x16x32_bf16 v[92:95], v[162:165], v[178:181], v[92:95]
	v_mfma_f32_16x16x32_bf16 v[88:91], v[170:173], v[178:181], v[88:91]
	v_mfma_f32_16x16x32_bf16 v[84:87], v[162:165], v[186:189], v[84:87]
	v_mfma_f32_16x16x32_bf16 v[80:83], v[170:173], v[186:189], v[80:83]
	v_mfma_f32_16x16x32_bf16 v[76:79], v[162:165], v[198:201], v[76:79]
	v_mfma_f32_16x16x32_bf16 v[72:75], v[170:173], v[198:201], v[72:75]
	v_mfma_f32_16x16x32_bf16 v[68:71], v[162:165], v[206:209], v[68:71]
	v_mfma_f32_16x16x32_bf16 v[64:67], v[170:173], v[206:209], v[64:67]
	v_mfma_f32_16x16x32_bf16 v[92:95], v[166:169], v[182:185], v[92:95]
	v_mfma_f32_16x16x32_bf16 v[88:91], v[174:177], v[182:185], v[88:91]
	v_mfma_f32_16x16x32_bf16 v[84:87], v[166:169], v[194:197], v[84:87]
	v_mfma_f32_16x16x32_bf16 v[80:83], v[174:177], v[194:197], v[80:83]
	v_mfma_f32_16x16x32_bf16 v[76:79], v[166:169], v[202:205], v[76:79]
	v_mfma_f32_16x16x32_bf16 v[72:75], v[174:177], v[202:205], v[72:75]
	v_mfma_f32_16x16x32_bf16 v[68:71], v[166:169], v[210:213], v[68:71]
	v_mfma_f32_16x16x32_bf16 v[64:67], v[174:177], v[210:213], v[64:67]
	s_setprio 0
	s_barrier
	s_add_i32 s26, s62, s91
	v_lshl_add_u64 v[190:191], s[30:31], 0, v[128:129]
	s_mov_b32 m0, s26
	ds_read_b128 v[178:181], v149 offset:16384
	ds_read_b128 v[182:185], v149 offset:17408
	ds_read_b128 v[186:189], v149 offset:18432
	ds_read_b128 v[194:197], v149 offset:19456
	ds_read_b128 v[198:201], v149 offset:20480
	ds_read_b128 v[202:205], v149 offset:21504
	ds_read_b128 v[206:209], v149 offset:22528
	ds_read_b128 v[210:213], v149 offset:23552
	global_load_lds_dwordx4 v[190:191], off
	s_add_i32 m0, s26, 0x2000
	s_add_u32 s26, s30, 0x2b0000
	v_lshl_add_u64 v[214:215], s[30:31], 0, v[130:131]
	s_addc_u32 s27, s31, 0
	s_add_i32 s97, s63, s91
	global_load_lds_dwordx4 v[214:215], off
	v_lshl_add_u64 v[216:217], s[26:27], 0, v[128:129]
	s_mov_b32 m0, s97
	v_lshl_add_u64 v[218:219], s[34:35], 0, v[130:131]
	global_load_lds_dwordx4 v[216:217], off
	v_lshl_add_u64 v[216:217], s[26:27], 0, v[130:131]
	s_add_i32 m0, s97, 0x2000
	s_nop 0
	global_load_lds_dwordx4 v[216:217], off
	v_lshl_add_u64 v[216:217], s[34:35], 0, v[128:129]
	s_mov_b32 m0, s5
	s_nop 0
	global_load_lds_dwordx4 v[216:217], off
	s_mov_b32 m0, s19
	s_nop 0
	global_load_lds_dwordx4 v[218:219], off
	s_waitcnt vmcnt(8)
	s_waitcnt lgkmcnt(0)
	s_barrier
; #define PG8_STAGE(bufoff, gbase, voff) do { _Pragma("unroll") for (int _i = 0; _i < 2; ++_i) \
;         __builtin_amdgcn_global_load_lds((const unsigned*)((const char*)(gbase) + (voff)[_i]), (LAS unsigned*)(lds + (bufoff) + ldsw + _i * 8192), 16, 0, 0); } while (0)
; #define PG8_LDA(dst, b, h) do { _Pragma("unroll") for (int m = 0; m < 4; ++m) _Pragma("unroll") for (int k = 0; k < 2; ++k) dst[m][k] = *(const LAS bf16x8*)(lds + PG8_SA(b, h) + aoff + m * 2048 + k * 1024); } while (0)
; #define PG8_LDB(dst, b, h) do { _Pragma("unroll") for (int n = 0; n < 2; ++n) _Pragma("unroll") for (int k = 0; k < 2; ++k) dst[n][k] = *(const LAS bf16x8*)(lds + PG8_SB(b, h) + boff + n * 2048 + k * 1024); } while (0)
; #define PG8_MMA(ai, bj, At, Bt) do { __builtin_amdgcn_s_setprio(1); _Pragma("unroll") for (int m = 0; m < 4; ++m) _Pragma("unroll") for (int n = 0; n < 2; ++n) _Pragma("unroll") for (int k = 0; k < 2; ++k) \
;         acc[ai][bj][m][n] = __builtin_amdgcn_mfma_f32_16x16x32_bf16(Bt[n][k], At[m][k], acc[ai][bj][m][n], 0, 0, 0); __builtin_amdgcn_s_setprio(0); } while (0)
; #define PG8_WAIT_V(n) asm volatile("s_waitcnt vmcnt(" #n ")" ::: "memory")
; #define PG8_WAIT_L(n) asm volatile("s_waitcnt lgkmcnt(" #n ")" ::: "memory")
; #define PG8_BAR __builtin_amdgcn_s_barrier()
; #define PG8_SCHED __builtin_amdgcn_sched_barrier(0)
; template <class Epi, class Sched>
; __device__ __forceinline__ void gemm_phase(LAS unsigned char* lds, const Gemm g, const Sched& S, const Epi& E, float* part, int wave) {
;     ...
;             PG8_WAIT_V(8); PG8_WAIT_L(0); PG8_BAR; PG8_MMA(1, 0, At, B0); PG8_MMA(1, 1, At, B1); PG8_BAR; PG8_SCHED;
;             PG8_LDB(B0, 1, 0); PG8_LDB(B1, 1, 1); PG8_SCHED; PG8_LDA(At, 1, 0); PG8_STAGE(PG8_SA(0, 1), a2 + hstep, voffA);
;             PG8_WAIT_V(8); PG8_WAIT_L(0); PG8_BAR; PG8_MMA(0, 0, At, B0); PG8_MMA(0, 1, At, B1); PG8_BAR; PG8_SCHED;
	s_setprio 1
	s_waitcnt lgkmcnt(0)
	v_mfma_f32_16x16x32_bf16 v[60:63], v[140:143], v[178:181], v[60:63]
	v_mfma_f32_16x16x32_bf16 v[56:59], v[154:157], v[178:181], v[56:59]
	v_mfma_f32_16x16x32_bf16 v[52:55], v[140:143], v[186:189], v[52:55]
	v_mfma_f32_16x16x32_bf16 v[48:51], v[154:157], v[186:189], v[48:51]
	v_mfma_f32_16x16x32_bf16 v[44:47], v[140:143], v[198:201], v[44:47]
	v_mfma_f32_16x16x32_bf16 v[40:43], v[154:157], v[198:201], v[40:43]
	v_mfma_f32_16x16x32_bf16 v[36:39], v[140:143], v[206:209], v[36:39]
	v_mfma_f32_16x16x32_bf16 v[32:35], v[154:157], v[206:209], v[32:35]
	v_mfma_f32_16x16x32_bf16 v[60:63], v[150:153], v[182:185], v[60:63]
	v_mfma_f32_16x16x32_bf16 v[56:59], v[158:161], v[182:185], v[56:59]
	v_mfma_f32_16x16x32_bf16 v[52:55], v[150:153], v[194:197], v[52:55]
	v_mfma_f32_16x16x32_bf16 v[48:51], v[158:161], v[194:197], v[48:51]
	v_mfma_f32_16x16x32_bf16 v[44:47], v[150:153], v[202:205], v[44:47]
	v_mfma_f32_16x16x32_bf16 v[40:43], v[158:161], v[202:205], v[40:43]
	v_mfma_f32_16x16x32_bf16 v[36:39], v[150:153], v[210:213], v[36:39]
	v_mfma_f32_16x16x32_bf16 v[32:35], v[158:161], v[210:213], v[32:35]
	s_setprio 0
	s_setprio 1
	v_mfma_f32_16x16x32_bf16 v[28:31], v[162:165], v[178:181], v[28:31]
	v_mfma_f32_16x16x32_bf16 v[24:27], v[170:173], v[178:181], v[24:27]
	v_mfma_f32_16x16x32_bf16 v[20:23], v[162:165], v[186:189], v[20:23]
	v_mfma_f32_16x16x32_bf16 v[16:19], v[170:173], v[186:189], v[16:19]
	v_mfma_f32_16x16x32_bf16 v[12:15], v[162:165], v[198:201], v[12:15]
	v_mfma_f32_16x16x32_bf16 v[8:11], v[170:173], v[198:201], v[8:11]
	v_mfma_f32_16x16x32_bf16 v[4:7], v[162:165], v[206:209], v[4:7]
	v_mfma_f32_16x16x32_bf16 v[0:3], v[170:173], v[206:209], v[0:3]
	v_mfma_f32_16x16x32_bf16 v[28:31], v[166:169], v[182:185], v[28:31]
	v_mfma_f32_16x16x32_bf16 v[24:27], v[174:177], v[182:185], v[24:27]
	v_mfma_f32_16x16x32_bf16 v[20:23], v[166:169], v[194:197], v[20:23]
	v_mfma_f32_16x16x32_bf16 v[16:19], v[174:177], v[194:197], v[16:19]
	v_mfma_f32_16x16x32_bf16 v[12:15], v[166:169], v[202:205], v[12:15]
	v_mfma_f32_16x16x32_bf16 v[8:11], v[174:177], v[202:205], v[8:11]
	v_mfma_f32_16x16x32_bf16 v[4:7], v[166:169], v[210:213], v[4:7]
	v_mfma_f32_16x16x32_bf16 v[0:3], v[174:177], v[210:213], v[0:3]
	s_setprio 0
	s_barrier
	s_add_i32 s97, 0, 0x18000
	s_add_i32 vcc_lo, 0, 0x1c000
	v_add_u32_e32 v158, s97, v145
	v_add_u32_e32 v174, vcc_lo, v145
	ds_read_b128 v[140:143], v158
	ds_read_b128 v[150:153], v158 offset:1024
	ds_read_b128 v[154:157], v158 offset:2048
	ds_read_b128 v[158:161], v158 offset:3072
	ds_read_b128 v[162:165], v174
	ds_read_b128 v[166:169], v174 offset:1024
	ds_read_b128 v[170:173], v174 offset:2048
	ds_read_b128 v[174:177], v174 offset:3072
	s_add_u32 s26, s34, 0x2b0000
	s_addc_u32 s27, s35, 0
	s_mov_b32 m0, s33
	v_lshl_add_u64 v[220:221], s[26:27], 0, v[128:129]
	ds_read_b128 v[178:181], v149 offset:32768
	ds_read_b128 v[182:185], v149 offset:33792
	ds_read_b128 v[186:189], v149 offset:34816
	ds_read_b128 v[194:197], v149 offset:35840
	ds_read_b128 v[198:201], v149 offset:36864
	ds_read_b128 v[202:205], v149 offset:37888
	ds_read_b128 v[206:209], v149 offset:38912
	ds_read_b128 v[210:213], v149 offset:39936
	global_load_lds_dwordx4 v[220:221], off
	v_lshl_add_u64 v[220:221], s[26:27], 0, v[130:131]
	s_mov_b32 m0, s36
	s_nop 0
	global_load_lds_dwordx4 v[220:221], off
	s_waitcnt vmcnt(8)
	s_waitcnt lgkmcnt(0)
	s_barrier
	s_setprio 1
	s_waitcnt lgkmcnt(0)
	v_mfma_f32_16x16x32_bf16 v[124:127], v[140:143], v[178:181], v[124:127]
	v_mfma_f32_16x16x32_bf16 v[120:123], v[154:157], v[178:181], v[120:123]
	v_mfma_f32_16x16x32_bf16 v[116:119], v[140:143], v[186:189], v[116:119]
	v_mfma_f32_16x16x32_bf16 v[112:115], v[154:157], v[186:189], v[112:115]
	v_mfma_f32_16x16x32_bf16 v[108:111], v[140:143], v[198:201], v[108:111]
	v_mfma_f32_16x16x32_bf16 v[104:107], v[154:157], v[198:201], v[104:107]
	v_mfma_f32_16x16x32_bf16 v[100:103], v[140:143], v[206:209], v[100:103]
	v_mfma_f32_16x16x32_bf16 v[96:99], v[154:157], v[206:209], v[96:99]
	v_mfma_f32_16x16x32_bf16 v[124:127], v[150:153], v[182:185], v[124:127]
	v_mfma_f32_16x16x32_bf16 v[120:123], v[158:161], v[182:185], v[120:123]
	v_mfma_f32_16x16x32_bf16 v[116:119], v[150:153], v[194:197], v[116:119]
	v_mfma_f32_16x16x32_bf16 v[112:115], v[158:161], v[194:197], v[112:115]
	v_mfma_f32_16x16x32_bf16 v[108:111], v[150:153], v[202:205], v[108:111]
	v_mfma_f32_16x16x32_bf16 v[104:107], v[158:161], v[202:205], v[104:107]
	v_mfma_f32_16x16x32_bf16 v[100:103], v[150:153], v[210:213], v[100:103]
	v_mfma_f32_16x16x32_bf16 v[96:99], v[158:161], v[210:213], v[96:99]
	s_setprio 0
	s_setprio 1
	v_mfma_f32_16x16x32_bf16 v[92:95], v[162:165], v[178:181], v[92:95]
	v_mfma_f32_16x16x32_bf16 v[88:91], v[170:173], v[178:181], v[88:91]
	v_mfma_f32_16x16x32_bf16 v[84:87], v[162:165], v[186:189], v[84:87]
	v_mfma_f32_16x16x32_bf16 v[80:83], v[170:173], v[186:189], v[80:83]
	v_mfma_f32_16x16x32_bf16 v[76:79], v[162:165], v[198:201], v[76:79]
	v_mfma_f32_16x16x32_bf16 v[72:75], v[170:173], v[198:201], v[72:75]
	v_mfma_f32_16x16x32_bf16 v[68:71], v[162:165], v[206:209], v[68:71]
	v_mfma_f32_16x16x32_bf16 v[64:67], v[170:173], v[206:209], v[64:67]
	v_mfma_f32_16x16x32_bf16 v[92:95], v[166:169], v[182:185], v[92:95]
	v_mfma_f32_16x16x32_bf16 v[88:91], v[174:177], v[182:185], v[88:91]
	v_mfma_f32_16x16x32_bf16 v[84:87], v[166:169], v[194:197], v[84:87]
	v_mfma_f32_16x16x32_bf16 v[80:83], v[174:177], v[194:197], v[80:83]
	v_mfma_f32_16x16x32_bf16 v[76:79], v[166:169], v[202:205], v[76:79]
	v_mfma_f32_16x16x32_bf16 v[72:75], v[174:177], v[202:205], v[72:75]
	v_mfma_f32_16x16x32_bf16 v[68:71], v[166:169], v[210:213], v[68:71]
	v_mfma_f32_16x16x32_bf16 v[64:67], v[174:177], v[210:213], v[64:67]
	s_setprio 0
	s_barrier
; #define PG8_STAGE(bufoff, gbase, voff) do { _Pragma("unroll") for (int _i = 0; _i < 2; ++_i) \
;         __builtin_amdgcn_global_load_lds((const unsigned*)((const char*)(gbase) + (voff)[_i]), (LAS unsigned*)(lds + (bufoff) + ldsw + _i * 8192), 16, 0, 0); } while (0)
; #define PG8_LDA(dst, b, h) do { _Pragma("unroll") for (int m = 0; m < 4; ++m) _Pragma("unroll") for (int k = 0; k < 2; ++k) dst[m][k] = *(const LAS bf16x8*)(lds + PG8_SA(b, h) + aoff + m * 2048 + k * 1024); } while (0)
; #define PG8_MMA(ai, bj, At, Bt) do { __builtin_amdgcn_s_setprio(1); _Pragma("unroll") for (int m = 0; m < 4; ++m) _Pragma("unroll") for (int n = 0; n < 2; ++n) _Pragma("unroll") for (int k = 0; k < 2; ++k) \
;         acc[ai][bj][m][n] = __builtin_amdgcn_mfma_f32_16x16x32_bf16(Bt[n][k], At[m][k], acc[ai][bj][m][n], 0, 0, 0); __builtin_amdgcn_s_setprio(0); } while (0)
; #define PG8_WAIT_V(n) asm volatile("s_waitcnt vmcnt(" #n ")" ::: "memory")
; #define PG8_WAIT_L(n) asm volatile("s_waitcnt lgkmcnt(" #n ")" ::: "memory")
; #define PG8_BAR __builtin_amdgcn_s_barrier()
; #define PG8_SCHED __builtin_amdgcn_sched_barrier(0)
; template <class Epi, class Sched>
; __device__ __forceinline__ void gemm_phase(LAS unsigned char* lds, const Gemm g, const Sched& S, const Epi& E, float* part, int wave) {
;     ...
;             PG8_LDA(At, 1, 1); PG8_STAGE(PG8_SB(1, 0), b3, voffB); PG8_STAGE(PG8_SB(1, 1), b3 + hstep, voffB); PG8_STAGE(PG8_SA(1, 0), a3, voffA);
;             PG8_WAIT_V(8); PG8_WAIT_L(0); PG8_BAR; PG8_MMA(1, 0, At, B0); PG8_MMA(1, 1, At, B1); PG8_BAR; PG8_SCHED;
;         }
	s_add_i32 s26, s97, s91
	v_lshl_add_u64 v[190:191], v[190:191], 0, s[14:15]
	s_mov_b32 m0, s26
	ds_read_b128 v[178:181], v149 offset:49152
	ds_read_b128 v[182:185], v149 offset:50176
	ds_read_b128 v[186:189], v149 offset:51200
	ds_read_b128 v[194:197], v149 offset:52224
	ds_read_b128 v[198:201], v149 offset:53248
	ds_read_b128 v[202:205], v149 offset:54272
	ds_read_b128 v[206:209], v149 offset:55296
	ds_read_b128 v[210:213], v149 offset:56320
	global_load_lds_dwordx4 v[190:191], off
	s_add_i32 m0, s26, 0x2000
	s_add_u32 s26, s30, 0x2b0080
	v_lshl_add_u64 v[190:191], v[214:215], 0, s[14:15]
	s_addc_u32 s27, s31, 0
	s_add_i32 s30, vcc_lo, s91
	global_load_lds_dwordx4 v[190:191], off
	v_lshl_add_u64 v[190:191], s[26:27], 0, v[128:129]
	s_mov_b32 m0, s30
	s_nop 0
	global_load_lds_dwordx4 v[190:191], off
	v_lshl_add_u64 v[190:191], s[26:27], 0, v[130:131]
	s_add_i32 m0, s30, 0x2000
	s_nop 0
	global_load_lds_dwordx4 v[190:191], off
	v_lshl_add_u64 v[190:191], v[216:217], 0, s[14:15]
	s_mov_b32 m0, s37
	s_nop 0
	global_load_lds_dwordx4 v[190:191], off
	v_lshl_add_u64 v[190:191], v[218:219], 0, s[14:15]
	s_mov_b32 m0, s39
	s_nop 0
	global_load_lds_dwordx4 v[190:191], off
	s_waitcnt vmcnt(8)
	s_waitcnt lgkmcnt(0)
	s_barrier
	s_setprio 1
	s_waitcnt lgkmcnt(0)
	v_mfma_f32_16x16x32_bf16 v[60:63], v[140:143], v[178:181], v[60:63]
	v_mfma_f32_16x16x32_bf16 v[56:59], v[154:157], v[178:181], v[56:59]
	v_mfma_f32_16x16x32_bf16 v[52:55], v[140:143], v[186:189], v[52:55]
	v_mfma_f32_16x16x32_bf16 v[48:51], v[154:157], v[186:189], v[48:51]
	v_mfma_f32_16x16x32_bf16 v[44:47], v[140:143], v[198:201], v[44:47]
	v_mfma_f32_16x16x32_bf16 v[40:43], v[154:157], v[198:201], v[40:43]
	v_mfma_f32_16x16x32_bf16 v[36:39], v[140:143], v[206:209], v[36:39]
	v_mfma_f32_16x16x32_bf16 v[32:35], v[154:157], v[206:209], v[32:35]
	v_mfma_f32_16x16x32_bf16 v[60:63], v[150:153], v[182:185], v[60:63]
	v_mfma_f32_16x16x32_bf16 v[56:59], v[158:161], v[182:185], v[56:59]
	v_mfma_f32_16x16x32_bf16 v[52:55], v[150:153], v[194:197], v[52:55]
	v_mfma_f32_16x16x32_bf16 v[48:51], v[158:161], v[194:197], v[48:51]
	v_mfma_f32_16x16x32_bf16 v[44:47], v[150:153], v[202:205], v[44:47]
	v_mfma_f32_16x16x32_bf16 v[40:43], v[158:161], v[202:205], v[40:43]
	v_mfma_f32_16x16x32_bf16 v[36:39], v[150:153], v[210:213], v[36:39]
	v_mfma_f32_16x16x32_bf16 v[32:35], v[158:161], v[210:213], v[32:35]
	s_setprio 0
	s_setprio 1
	v_mfma_f32_16x16x32_bf16 v[28:31], v[162:165], v[178:181], v[28:31]
	v_mfma_f32_16x16x32_bf16 v[24:27], v[170:173], v[178:181], v[24:27]
	v_mfma_f32_16x16x32_bf16 v[20:23], v[162:165], v[186:189], v[20:23]
	v_mfma_f32_16x16x32_bf16 v[16:19], v[170:173], v[186:189], v[16:19]
	v_mfma_f32_16x16x32_bf16 v[12:15], v[162:165], v[198:201], v[12:15]
	v_mfma_f32_16x16x32_bf16 v[8:11], v[170:173], v[198:201], v[8:11]
	v_mfma_f32_16x16x32_bf16 v[4:7], v[162:165], v[206:209], v[4:7]
	v_mfma_f32_16x16x32_bf16 v[0:3], v[170:173], v[206:209], v[0:3]
	v_mfma_f32_16x16x32_bf16 v[28:31], v[166:169], v[182:185], v[28:31]
	v_mfma_f32_16x16x32_bf16 v[24:27], v[174:177], v[182:185], v[24:27]
	v_mfma_f32_16x16x32_bf16 v[20:23], v[166:169], v[194:197], v[20:23]
	v_mfma_f32_16x16x32_bf16 v[16:19], v[174:177], v[194:197], v[16:19]
	v_mfma_f32_16x16x32_bf16 v[12:15], v[166:169], v[202:205], v[12:15]
	v_mfma_f32_16x16x32_bf16 v[8:11], v[174:177], v[202:205], v[8:11]
	v_mfma_f32_16x16x32_bf16 v[4:7], v[166:169], v[210:213], v[4:7]
	v_mfma_f32_16x16x32_bf16 v[0:3], v[174:177], v[210:213], v[0:3]
	s_add_u32 s94, s94, 0x100
	s_addc_u32 s95, s95, 0
	s_cmp_ge_i32 s96, s21
	s_mov_b64 s[26:27], s[28:29]
	s_mov_b32 s30, s96
	s_setprio 0
	s_barrier
	s_cbranch_scc0 .LBB0_1249
	s_and_b64 vcc, exec, s[48:49]
	s_cbranch_vccz .LBB0_1255
